# P0a: item stores deferred behind the next item's 32 tile loads (decouples load waits from store acks under in-order vmcnt), on p0map+p0a
# baseline (speedup 1.0000x reference)
.LBB0_8:
	s_or_b64 exec, exec, s[6:7]
	s_cmp_lt_i32 s30, 1
	s_cselect_b64 s[4:5], -1, 0
	s_cmp_gt_i32 s31, 0
	s_cselect_b64 s[6:7], -1, 0
	s_and_b64 s[4:5], s[4:5], s[6:7]
	s_and_b64 vcc, exec, s[4:5]
	s_cbranch_vccz .LBB0_190
	s_mov_b64 s[74:75], 0
	s_mov_b64 s[76:77], 0
	s_mov_b64 s[72:73], 0x800
	s_mov_b64 s[12:13], s[0:1]
	s_load_dwordx2 s[14:15], s[12:13], 0xe0
	v_mov_b32_e32 v36, v0
	s_lshl_b32 s4, s48, 3
	v_ashrrev_i32_e32 v39, 6, v36
	v_and_b32_e32 v41, 63, v36
	v_readfirstlane_b32 s3, v39
	s_add_i32 s4, s3, s4
	s_cmp_gt_i32 s4, 0x1667f
	s_cbranch_scc1 .LBB0_86
	v_lshlrev_b32_e32 v1, 4, v41
	s_lshl_b32 s8, s3, 14
	v_and_b32_e32 v40, 31, v36
	v_and_b32_e32 v34, 48, v1
	s_add_i32 s9, s8, 0
	v_lshlrev_b32_e32 v42, 2, v40
	v_mul_u32_u24_e32 v1, 0x84, v34
	v_and_b32_e32 v4, 60, v41
	v_add_u32_e32 v44, s9, v42
	s_movk_i32 s21, 0x84
	v_add3_u32 v59, s9, v1, v4
	v_and_b32_e32 v1, 32, v36
	v_mad_u32_u24 v63, v1, s21, v44
	v_lshlrev_b32_e32 v1, 3, v41
	v_mov_b32_e32 v35, 0
	v_and_b32_e32 v1, 56, v1
	s_waitcnt lgkmcnt(0)
	v_lshl_add_u64 v[2:3], s[14:15], 0, v[34:35]
	s_mov_b64 s[6:7], 0xa800000
	v_lshlrev_b32_e32 v34, 1, v1
	v_lshl_add_u64 v[46:47], v[2:3], 0, s[6:7]
	v_lshl_add_u64 v[4:5], s[14:15], 0, v[34:35]
	s_mov_b64 s[6:7], 0x800000
	v_lshl_add_u64 v[48:49], v[4:5], 0, s[6:7]
	s_mov_b64 s[6:7], 0x16c00000
	v_lshl_add_u64 v[50:51], v[2:3], 0, s[6:7]
	s_mov_b64 s[6:7], 0x16600000
	s_lshl_b32 s5, s34, 3
	v_lshrrev_b32_e32 v38, 5, v41
	v_lshl_add_u64 v[52:53], v[2:3], 0, s[6:7]
	s_mov_b64 s[6:7], 0x44c00000
	s_add_u32 s18, s14, 0x2800000
	v_lshrrev_b32_e32 v64, 3, v41
	v_lshl_add_u64 v[54:55], v[2:3], 0, s[6:7]
	s_mov_b64 s[6:7], 0x12800000
	v_mul_u32_u24_e32 v2, 0x84, v38
	v_lshrrev_b32_e32 v45, 2, v41
	s_addc_u32 s19, s15, 0
	v_mul_u32_u24_e32 v6, 0x84, v1
	v_lshlrev_b32_e32 v1, 2, v64
	v_lshl_add_u64 v[56:57], v[4:5], 0, s[6:7]
	v_or_b32_e32 v2, s8, v2
	s_lshl_b32 s6, s48, 8
	s_lshl_b32 s7, s3, 5
	s_mov_b32 s17, 0
	v_or_b32_e32 v62, 16, v45
	v_add3_u32 v65, s9, v6, v1
	v_or_b32_e32 v66, 8, v64
	v_or_b32_e32 v67, 16, v64
	v_or_b32_e32 v68, 24, v64
	v_mov_b32_e32 v1, v38
	v_add3_u32 v69, v2, v42, 0
	v_mov_b32_e32 v43, v35
	s_add_i32 s25, s6, s7
	s_lshl_b32 s35, s34, 8
	v_or_b32_e32 v70, 14, v38
	s_add_i32 s38, s4, 0xbd80
	v_lshlrev_b32_e32 v58, 2, v38
	v_mov_b32_e32 v37, v35
	v_or_b32_e32 v71, 12, v38
	v_or_b32_e32 v72, 10, v38
	v_or_b32_e32 v73, 8, v38
	v_or_b32_e32 v74, 6, v38
	v_or_b32_e32 v75, 4, v38
	v_or_b32_e32 v76, 2, v38
	s_mov_b32 s20, 0x43000000
	s_mov_b32 s39, 0xc3e00000
	s_mov_b32 s40, 0xc0f00000
	s_mov_b64 s[22:23], 0x800800
	s_movk_i32 s41, 0x7fff
	s_mov_b32 s42, 0xffff0000
	s_movk_i32 s43, 0x3000
	s_movk_i32 s46, 0x7900
	s_mov_b32 s24, 0x42800000
	v_lshlrev_b32_e32 v60, 2, v40
	v_mov_b32_e32 v77, 0x43e00000
	v_mov_b32_e32 v78, 0x40f00000
	s_branch .LBB0_12

.LBB0_18:
	s_mov_b32 s62, 0x4000
	s_mov_b32 s66, 0x8000
	s_mov_b32 s67, 0
	v_mad_u32_u24 v142, v38, s21, v44
	v_mad_u64_u32 v[140:141], s[64:65], v4, s62, v[2:3]
	global_load_dword v100, v[140:141], off
	v_lshl_add_u64 v[140:141], v[140:141], 0, s[66:67]
	global_load_dword v101, v[140:141], off
	v_lshl_add_u64 v[140:141], v[140:141], 0, s[66:67]
	global_load_dword v102, v[140:141], off
	v_lshl_add_u64 v[140:141], v[140:141], 0, s[66:67]
	global_load_dword v103, v[140:141], off
	v_lshl_add_u64 v[140:141], v[140:141], 0, s[66:67]
	global_load_dword v104, v[140:141], off
	v_lshl_add_u64 v[140:141], v[140:141], 0, s[66:67]
	global_load_dword v105, v[140:141], off
	v_lshl_add_u64 v[140:141], v[140:141], 0, s[66:67]
	global_load_dword v106, v[140:141], off
	v_lshl_add_u64 v[140:141], v[140:141], 0, s[66:67]
	global_load_dword v107, v[140:141], off
	v_lshl_add_u64 v[140:141], v[140:141], 0, s[66:67]
	global_load_dword v108, v[140:141], off
	v_lshl_add_u64 v[140:141], v[140:141], 0, s[66:67]
	global_load_dword v109, v[140:141], off
	v_lshl_add_u64 v[140:141], v[140:141], 0, s[66:67]
	global_load_dword v110, v[140:141], off
	v_lshl_add_u64 v[140:141], v[140:141], 0, s[66:67]
	global_load_dword v111, v[140:141], off
	v_lshl_add_u64 v[140:141], v[140:141], 0, s[66:67]
	global_load_dword v112, v[140:141], off
	v_lshl_add_u64 v[140:141], v[140:141], 0, s[66:67]
	global_load_dword v113, v[140:141], off
	v_lshl_add_u64 v[140:141], v[140:141], 0, s[66:67]
	global_load_dword v114, v[140:141], off
	v_lshl_add_u64 v[140:141], v[140:141], 0, s[66:67]
	global_load_dword v115, v[140:141], off
	v_lshl_add_u64 v[140:141], v[140:141], 0, s[66:67]
	global_load_dword v116, v[140:141], off
	v_lshl_add_u64 v[140:141], v[140:141], 0, s[66:67]
	global_load_dword v117, v[140:141], off
	v_lshl_add_u64 v[140:141], v[140:141], 0, s[66:67]
	global_load_dword v118, v[140:141], off
	v_lshl_add_u64 v[140:141], v[140:141], 0, s[66:67]
	global_load_dword v119, v[140:141], off
	v_lshl_add_u64 v[140:141], v[140:141], 0, s[66:67]
	global_load_dword v120, v[140:141], off
	v_lshl_add_u64 v[140:141], v[140:141], 0, s[66:67]
	global_load_dword v121, v[140:141], off
	v_lshl_add_u64 v[140:141], v[140:141], 0, s[66:67]
	global_load_dword v122, v[140:141], off
	v_lshl_add_u64 v[140:141], v[140:141], 0, s[66:67]
	global_load_dword v123, v[140:141], off
	v_lshl_add_u64 v[140:141], v[140:141], 0, s[66:67]
	global_load_dword v124, v[140:141], off
	v_lshl_add_u64 v[140:141], v[140:141], 0, s[66:67]
	global_load_dword v125, v[140:141], off
	v_lshl_add_u64 v[140:141], v[140:141], 0, s[66:67]
	global_load_dword v126, v[140:141], off
	v_lshl_add_u64 v[140:141], v[140:141], 0, s[66:67]
	global_load_dword v127, v[140:141], off
	v_lshl_add_u64 v[140:141], v[140:141], 0, s[66:67]
	global_load_dword v128, v[140:141], off
	v_lshl_add_u64 v[140:141], v[140:141], 0, s[66:67]
	global_load_dword v129, v[140:141], off
	v_lshl_add_u64 v[140:141], v[140:141], 0, s[66:67]
	global_load_dword v130, v[140:141], off
	v_lshl_add_u64 v[140:141], v[140:141], 0, s[66:67]
	global_load_dword v131, v[140:141], off
	s_and_saveexec_b64 s[70:71], s[74:75]
	global_store_dwordx4 v[144:145], v[146:149], off
	global_store_dwordx4 v[150:151], v[152:155], off
	s_mov_b64 exec, s[70:71]
	s_and_saveexec_b64 s[70:71], s[76:77]
	global_store_dwordx4 v[156:157], v[158:161], off
	global_store_dwordx4 v[162:163], v[164:167], off
	s_mov_b64 exec, s[70:71]
	s_mov_b64 s[74:75], 0
	s_mov_b64 s[76:77], 0
	s_waitcnt vmcnt(32)
	v_pk_mul_f32 v[100:101], v[100:101], s[20:21] op_sel_hi:[1,0]
	v_pk_mul_f32 v[102:103], v[102:103], s[20:21] op_sel_hi:[1,0]
	ds_write_b32 v142, v100
	ds_write_b32 v142, v101 offset:264
	ds_write_b32 v142, v102 offset:528
	ds_write_b32 v142, v103 offset:792
	s_waitcnt vmcnt(28)
	v_pk_mul_f32 v[104:105], v[104:105], s[20:21] op_sel_hi:[1,0]
	v_pk_mul_f32 v[106:107], v[106:107], s[20:21] op_sel_hi:[1,0]
	ds_write_b32 v142, v104 offset:1056
	ds_write_b32 v142, v105 offset:1320
	ds_write_b32 v142, v106 offset:1584
	ds_write_b32 v142, v107 offset:1848
	s_waitcnt vmcnt(24)
	v_pk_mul_f32 v[108:109], v[108:109], s[20:21] op_sel_hi:[1,0]
	v_pk_mul_f32 v[110:111], v[110:111], s[20:21] op_sel_hi:[1,0]
	ds_write_b32 v142, v108 offset:2112
	ds_write_b32 v142, v109 offset:2376
	ds_write_b32 v142, v110 offset:2640
	ds_write_b32 v142, v111 offset:2904
	s_waitcnt vmcnt(20)
	v_pk_mul_f32 v[112:113], v[112:113], s[20:21] op_sel_hi:[1,0]
	v_pk_mul_f32 v[114:115], v[114:115], s[20:21] op_sel_hi:[1,0]
	ds_write_b32 v142, v112 offset:3168
	ds_write_b32 v142, v113 offset:3432
	ds_write_b32 v142, v114 offset:3696
	ds_write_b32 v142, v115 offset:3960
	s_waitcnt vmcnt(16)
	v_pk_mul_f32 v[116:117], v[116:117], s[20:21] op_sel_hi:[1,0]
	v_pk_mul_f32 v[118:119], v[118:119], s[20:21] op_sel_hi:[1,0]
	ds_write_b32 v142, v116 offset:4224
	ds_write_b32 v142, v117 offset:4488
	ds_write_b32 v142, v118 offset:4752
	ds_write_b32 v142, v119 offset:5016
	s_waitcnt vmcnt(12)
	v_pk_mul_f32 v[120:121], v[120:121], s[20:21] op_sel_hi:[1,0]
	v_pk_mul_f32 v[122:123], v[122:123], s[20:21] op_sel_hi:[1,0]
	ds_write_b32 v142, v120 offset:5280
	ds_write_b32 v142, v121 offset:5544
	ds_write_b32 v142, v122 offset:5808
	ds_write_b32 v142, v123 offset:6072
	s_waitcnt vmcnt(8)
	v_pk_mul_f32 v[124:125], v[124:125], s[20:21] op_sel_hi:[1,0]
	v_pk_mul_f32 v[126:127], v[126:127], s[20:21] op_sel_hi:[1,0]
	ds_write_b32 v142, v124 offset:6336
	ds_write_b32 v142, v125 offset:6600
	ds_write_b32 v142, v126 offset:6864
	ds_write_b32 v142, v127 offset:7128
	s_waitcnt vmcnt(4)
	v_pk_mul_f32 v[128:129], v[128:129], s[20:21] op_sel_hi:[1,0]
	v_pk_mul_f32 v[130:131], v[130:131], s[20:21] op_sel_hi:[1,0]
	ds_write_b32 v142, v128 offset:7392
	ds_write_b32 v142, v129 offset:7656
	ds_write_b32 v142, v130 offset:7920
	ds_write_b32 v142, v131 offset:8184
	s_waitcnt lgkmcnt(0)
	ds_read2_b32 v[6:7], v59 offset1:16
	ds_read2_b32 v[8:9], v59 offset0:33 offset1:49
	ds_read2_b32 v[10:11], v59 offset0:66 offset1:82
	ds_read2_b32 v[12:13], v59 offset0:99 offset1:115
	ds_read2_b32 v[16:17], v59 offset0:132 offset1:148
	ds_read2_b32 v[18:19], v59 offset0:165 offset1:181
	ds_read2_b32 v[20:21], v59 offset0:198 offset1:214
	ds_read2_b32 v[22:23], v59 offset0:231 offset1:247
	s_waitcnt lgkmcnt(7)
	v_max_f32_e32 v2, v6, v6
	s_waitcnt lgkmcnt(6)
	v_max_f32_e32 v3, v8, v8
	v_med3_f32 v6, v2, s39, v77
	v_med3_f32 v3, v3, s39, v77
	v_mov_b32_e32 v2, v35
	v_cvt_pk_fp8_f32 v2, v6, v3
	s_waitcnt lgkmcnt(5)
	v_max_f32_e32 v4, v10, v10
	s_waitcnt lgkmcnt(4)
	v_max_f32_e32 v5, v12, v12
	v_med3_f32 v4, v4, s39, v77
	v_med3_f32 v5, v5, s39, v77
	v_cvt_pk_fp8_f32 v2, v4, v5 op_sel:[0,0,1]
	s_waitcnt lgkmcnt(3)
	v_max_f32_e32 v3, v16, v16
	s_waitcnt lgkmcnt(2)
	v_max_f32_e32 v4, v18, v18
	v_med3_f32 v8, v3, s39, v77
	v_med3_f32 v4, v4, s39, v77
	v_mov_b32_e32 v3, v35
	v_cvt_pk_fp8_f32 v3, v8, v4
	v_add_u32_e32 v8, 0x400, v59
	ds_read2_b32 v[24:25], v8 offset0:8 offset1:24
	ds_read2_b32 v[26:27], v8 offset0:41 offset1:57
	ds_read2_b32 v[28:29], v8 offset0:74 offset1:90
	ds_read2_b32 v[30:31], v8 offset0:107 offset1:123
	s_waitcnt lgkmcnt(5)
	v_max_f32_e32 v5, v20, v20
	s_waitcnt lgkmcnt(4)
	v_max_f32_e32 v6, v22, v22
	v_med3_f32 v5, v5, s39, v77
	v_med3_f32 v6, v6, s39, v77
	v_cvt_pk_fp8_f32 v3, v5, v6 op_sel:[0,0,1]
	s_waitcnt lgkmcnt(3)
	v_max_f32_e32 v4, v24, v24
	s_waitcnt lgkmcnt(2)
	v_max_f32_e32 v5, v26, v26
	v_med3_f32 v12, v4, s39, v77
	v_med3_f32 v5, v5, s39, v77
	v_mov_b32_e32 v4, v35
	v_cvt_pk_fp8_f32 v4, v12, v5
	ds_read2_b32 v[32:33], v8 offset0:140 offset1:156
	ds_read2_b32 v[80:81], v8 offset0:173 offset1:189
	ds_read2_b32 v[82:83], v8 offset0:206 offset1:222
	s_waitcnt lgkmcnt(4)
	v_max_f32_e32 v6, v28, v28
	s_waitcnt lgkmcnt(3)
	v_max_f32_e32 v10, v30, v30
	v_med3_f32 v6, v6, s39, v77
	v_med3_f32 v5, v10, s39, v77
	ds_read2_b32 v[84:85], v8 offset0:239 offset1:255
	v_cvt_pk_fp8_f32 v4, v6, v5 op_sel:[0,0,1]
	s_waitcnt lgkmcnt(3)
	v_max_f32_e32 v5, v32, v32
	s_waitcnt lgkmcnt(2)
	v_max_f32_e32 v6, v80, v80
	v_med3_f32 v8, v5, s39, v77
	v_med3_f32 v6, v6, s39, v77
	v_mov_b32_e32 v5, v35
	v_cvt_pk_fp8_f32 v5, v8, v6
	s_waitcnt lgkmcnt(1)
	v_max_f32_e32 v10, v82, v82
	s_waitcnt lgkmcnt(0)
	v_max_f32_e32 v6, v84, v84
	v_med3_f32 v8, v10, s39, v77
	v_med3_f32 v6, v6, s39, v77
	v_cvt_pk_fp8_f32 v5, v8, v6 op_sel:[0,0,1]
	v_or_b32_e32 v6, s6, v45
	v_lshl_add_u64 v[14:15], v[46:47], 0, s[16:17]
	v_lshlrev_b32_e32 v34, 14, v6
	v_lshl_add_u64 v[86:87], v[14:15], 0, v[34:35]
	v_lshl_add_u64 v[144:145], v[86:87], 0, 0
	v_mov_b32_e32 v146, v2
	v_mov_b32_e32 v147, v3
	v_mov_b32_e32 v148, v4
	v_mov_b32_e32 v149, v5
	s_nop 1
	v_max_f32_e32 v2, v7, v7
	v_max_f32_e32 v3, v9, v9
	v_med3_f32 v5, v2, s39, v77
	v_med3_f32 v3, v3, s39, v77
	v_mov_b32_e32 v2, v35
	v_cvt_pk_fp8_f32 v2, v5, v3
	v_max_f32_e32 v4, v11, v11
	v_max_f32_e32 v3, v13, v13
	v_med3_f32 v4, v4, s39, v77
	v_med3_f32 v3, v3, s39, v77
	v_cvt_pk_fp8_f32 v2, v4, v3 op_sel:[0,0,1]
	v_max_f32_e32 v3, v17, v17
	v_max_f32_e32 v4, v19, v19
	v_med3_f32 v6, v3, s39, v77
	v_med3_f32 v4, v4, s39, v77
	v_mov_b32_e32 v3, v35
	v_cvt_pk_fp8_f32 v3, v6, v4
	v_max_f32_e32 v5, v21, v21
	v_max_f32_e32 v4, v23, v23
	v_med3_f32 v5, v5, s39, v77
	v_med3_f32 v4, v4, s39, v77
	v_cvt_pk_fp8_f32 v3, v5, v4 op_sel:[0,0,1]
	v_max_f32_e32 v4, v25, v25
	v_max_f32_e32 v5, v27, v27
	v_med3_f32 v7, v4, s39, v77
	v_med3_f32 v5, v5, s39, v77
	v_mov_b32_e32 v4, v35
	v_cvt_pk_fp8_f32 v4, v7, v5
	v_max_f32_e32 v6, v29, v29
	v_max_f32_e32 v5, v31, v31
	v_med3_f32 v6, v6, s39, v77
	v_med3_f32 v5, v5, s39, v77
	v_cvt_pk_fp8_f32 v4, v6, v5 op_sel:[0,0,1]
	v_max_f32_e32 v5, v33, v33
	v_max_f32_e32 v6, v81, v81
	v_med3_f32 v8, v5, s39, v77
	v_med3_f32 v6, v6, s39, v77
	v_mov_b32_e32 v5, v35
	v_cvt_pk_fp8_f32 v5, v8, v6
	v_max_f32_e32 v7, v83, v83
	v_max_f32_e32 v6, v85, v85
	v_med3_f32 v7, v7, s39, v77
	v_med3_f32 v6, v6, s39, v77
	v_cvt_pk_fp8_f32 v5, v7, v6 op_sel:[0,0,1]
	v_or_b32_e32 v6, s6, v62
	v_lshlrev_b32_e32 v34, 14, v6
	v_lshl_add_u64 v[6:7], v[14:15], 0, v[34:35]
	v_lshl_add_u64 v[150:151], v[6:7], 0, 0
	v_mov_b32_e32 v152, v2
	v_mov_b32_e32 v153, v3
	v_mov_b32_e32 v154, v4
	v_mov_b32_e32 v155, v5
	s_mov_b64 s[74:75], -1
	s_mov_b64 s[76:77], 0
	s_waitcnt lgkmcnt(0)
	s_mov_b64 s[6:7], 0

.LBB0_22:
	s_mov_b32 s62, 0x10000
	s_mov_b32 s66, 0x20000
	s_mov_b32 s67, 0
	v_mad_u32_u24 v142, v38, s21, v44
	v_mad_u64_u32 v[140:141], s[64:65], v4, s62, v[2:3]
	global_load_dword v100, v[140:141], off
	v_lshl_add_u64 v[140:141], v[140:141], 0, s[66:67]
	global_load_dword v101, v[140:141], off
	v_lshl_add_u64 v[140:141], v[140:141], 0, s[66:67]
	global_load_dword v102, v[140:141], off
	v_lshl_add_u64 v[140:141], v[140:141], 0, s[66:67]
	global_load_dword v103, v[140:141], off
	v_lshl_add_u64 v[140:141], v[140:141], 0, s[66:67]
	global_load_dword v104, v[140:141], off
	v_lshl_add_u64 v[140:141], v[140:141], 0, s[66:67]
	global_load_dword v105, v[140:141], off
	v_lshl_add_u64 v[140:141], v[140:141], 0, s[66:67]
	global_load_dword v106, v[140:141], off
	v_lshl_add_u64 v[140:141], v[140:141], 0, s[66:67]
	global_load_dword v107, v[140:141], off
	v_lshl_add_u64 v[140:141], v[140:141], 0, s[66:67]
	global_load_dword v108, v[140:141], off
	v_lshl_add_u64 v[140:141], v[140:141], 0, s[66:67]
	global_load_dword v109, v[140:141], off
	v_lshl_add_u64 v[140:141], v[140:141], 0, s[66:67]
	global_load_dword v110, v[140:141], off
	v_lshl_add_u64 v[140:141], v[140:141], 0, s[66:67]
	global_load_dword v111, v[140:141], off
	v_lshl_add_u64 v[140:141], v[140:141], 0, s[66:67]
	global_load_dword v112, v[140:141], off
	v_lshl_add_u64 v[140:141], v[140:141], 0, s[66:67]
	global_load_dword v113, v[140:141], off
	v_lshl_add_u64 v[140:141], v[140:141], 0, s[66:67]
	global_load_dword v114, v[140:141], off
	v_lshl_add_u64 v[140:141], v[140:141], 0, s[66:67]
	global_load_dword v115, v[140:141], off
	v_lshl_add_u64 v[140:141], v[140:141], 0, s[66:67]
	global_load_dword v116, v[140:141], off
	v_lshl_add_u64 v[140:141], v[140:141], 0, s[66:67]
	global_load_dword v117, v[140:141], off
	v_lshl_add_u64 v[140:141], v[140:141], 0, s[66:67]
	global_load_dword v118, v[140:141], off
	v_lshl_add_u64 v[140:141], v[140:141], 0, s[66:67]
	global_load_dword v119, v[140:141], off
	v_lshl_add_u64 v[140:141], v[140:141], 0, s[66:67]
	global_load_dword v120, v[140:141], off
	v_lshl_add_u64 v[140:141], v[140:141], 0, s[66:67]
	global_load_dword v121, v[140:141], off
	v_lshl_add_u64 v[140:141], v[140:141], 0, s[66:67]
	global_load_dword v122, v[140:141], off
	v_lshl_add_u64 v[140:141], v[140:141], 0, s[66:67]
	global_load_dword v123, v[140:141], off
	v_lshl_add_u64 v[140:141], v[140:141], 0, s[66:67]
	global_load_dword v124, v[140:141], off
	v_lshl_add_u64 v[140:141], v[140:141], 0, s[66:67]
	global_load_dword v125, v[140:141], off
	v_lshl_add_u64 v[140:141], v[140:141], 0, s[66:67]
	global_load_dword v126, v[140:141], off
	v_lshl_add_u64 v[140:141], v[140:141], 0, s[66:67]
	global_load_dword v127, v[140:141], off
	v_lshl_add_u64 v[140:141], v[140:141], 0, s[66:67]
	global_load_dword v128, v[140:141], off
	v_lshl_add_u64 v[140:141], v[140:141], 0, s[66:67]
	global_load_dword v129, v[140:141], off
	v_lshl_add_u64 v[140:141], v[140:141], 0, s[66:67]
	global_load_dword v130, v[140:141], off
	v_lshl_add_u64 v[140:141], v[140:141], 0, s[66:67]
	global_load_dword v131, v[140:141], off
	s_and_saveexec_b64 s[70:71], s[74:75]
	global_store_dwordx4 v[144:145], v[146:149], off
	global_store_dwordx4 v[150:151], v[152:155], off
	s_mov_b64 exec, s[70:71]
	s_and_saveexec_b64 s[70:71], s[76:77]
	global_store_dwordx4 v[156:157], v[158:161], off
	global_store_dwordx4 v[162:163], v[164:167], off
	s_mov_b64 exec, s[70:71]
	s_mov_b64 s[74:75], 0
	s_mov_b64 s[76:77], 0
	s_waitcnt vmcnt(32)
	ds_write_b32 v142, v100
	ds_write_b32 v142, v101 offset:264
	ds_write_b32 v142, v102 offset:528
	ds_write_b32 v142, v103 offset:792
	s_waitcnt vmcnt(28)
	ds_write_b32 v142, v104 offset:1056
	ds_write_b32 v142, v105 offset:1320
	ds_write_b32 v142, v106 offset:1584
	ds_write_b32 v142, v107 offset:1848
	s_waitcnt vmcnt(24)
	ds_write_b32 v142, v108 offset:2112
	ds_write_b32 v142, v109 offset:2376
	ds_write_b32 v142, v110 offset:2640
	ds_write_b32 v142, v111 offset:2904
	s_waitcnt vmcnt(20)
	ds_write_b32 v142, v112 offset:3168
	ds_write_b32 v142, v113 offset:3432
	ds_write_b32 v142, v114 offset:3696
	ds_write_b32 v142, v115 offset:3960
	s_waitcnt vmcnt(16)
	ds_write_b32 v142, v116 offset:4224
	ds_write_b32 v142, v117 offset:4488
	ds_write_b32 v142, v118 offset:4752
	ds_write_b32 v142, v119 offset:5016
	s_waitcnt vmcnt(12)
	ds_write_b32 v142, v120 offset:5280
	ds_write_b32 v142, v121 offset:5544
	ds_write_b32 v142, v122 offset:5808
	ds_write_b32 v142, v123 offset:6072
	s_waitcnt vmcnt(8)
	ds_write_b32 v142, v124 offset:6336
	ds_write_b32 v142, v125 offset:6600
	ds_write_b32 v142, v126 offset:6864
	ds_write_b32 v142, v127 offset:7128
	s_waitcnt vmcnt(4)
	ds_write_b32 v142, v128 offset:7392
	ds_write_b32 v142, v129 offset:7656
	ds_write_b32 v142, v130 offset:7920
	ds_write_b32 v142, v131 offset:8184
	s_waitcnt lgkmcnt(0)
	ds_read2_b32 v[2:3], v63 offset1:33
	v_add_u32_e32 v16, 0x800, v63
	v_add_u32_e32 v18, 0x400, v63
	v_add_u32_e32 v19, 0xc00, v63
	ds_read2_b32 v[4:5], v16 offset0:16 offset1:49
	ds_read2_b32 v[6:7], v63 offset0:66 offset1:99
	ds_read2_b32 v[8:9], v16 offset0:82 offset1:115
	ds_read2_b32 v[10:11], v63 offset0:132 offset1:165
	ds_read2_b32 v[12:13], v16 offset0:148 offset1:181
	ds_read2_b32 v[14:15], v63 offset0:198 offset1:231
	ds_read2_b32 v[16:17], v16 offset0:214 offset1:247
	ds_read2_b32 v[26:27], v18 offset0:8 offset1:41
	ds_read2_b32 v[28:29], v19 offset0:24 offset1:57
	ds_read2_b32 v[30:31], v18 offset0:74 offset1:107
	ds_read2_b32 v[32:33], v19 offset0:90 offset1:123
	ds_read2_b32 v[80:81], v18 offset0:140 offset1:173
	ds_read2_b32 v[82:83], v19 offset0:156 offset1:189
	ds_read2_b32 v[84:85], v18 offset0:206 offset1:239
	ds_read2_b32 v[86:87], v19 offset0:222 offset1:255
	s_waitcnt lgkmcnt(14)
	v_max_f32_e64 v18, |v4|, |v4|
	v_max_f32_e64 v19, |v2|, |v2|
	v_max_f32_e32 v18, v19, v18
	v_max_f32_e64 v19, |v5|, |v5|
	v_max_f32_e64 v20, |v3|, |v3|
	v_max_f32_e32 v19, v20, v19
	v_max3_f32 v18, v18, 0, v19
	s_waitcnt lgkmcnt(12)
	v_max_f32_e64 v19, |v8|, |v8|
	v_max_f32_e64 v20, |v6|, |v6|
	v_max_f32_e32 v19, v20, v19
	v_max_f32_e64 v20, |v9|, |v9|
	v_max_f32_e64 v21, |v7|, |v7|
	v_max_f32_e32 v20, v21, v20
	v_max3_f32 v18, v18, v19, v20
	s_waitcnt lgkmcnt(10)
	v_max_f32_e64 v19, |v12|, |v12|
	v_max_f32_e64 v20, |v10|, |v10|
	v_max_f32_e32 v19, v20, v19
	v_max_f32_e64 v20, |v13|, |v13|
	v_max_f32_e64 v21, |v11|, |v11|
	v_max_f32_e32 v20, v21, v20
	v_max3_f32 v18, v18, v19, v20
	s_waitcnt lgkmcnt(8)
	v_max_f32_e64 v19, |v16|, |v16|
	v_max_f32_e64 v20, |v14|, |v14|
	v_max_f32_e32 v19, v20, v19
	v_max_f32_e64 v20, |v17|, |v17|
	v_max_f32_e64 v21, |v15|, |v15|
	v_max_f32_e32 v20, v21, v20
	v_max3_f32 v18, v18, v19, v20
	s_waitcnt lgkmcnt(6)
	v_max_f32_e64 v19, |v28|, |v28|
	v_max_f32_e64 v20, |v26|, |v26|
	v_max_f32_e32 v19, v20, v19
	v_max_f32_e64 v20, |v29|, |v29|
	v_max_f32_e64 v21, |v27|, |v27|
	v_max_f32_e32 v20, v21, v20
	v_max3_f32 v18, v18, v19, v20
	s_waitcnt lgkmcnt(4)
	v_max_f32_e64 v19, |v32|, |v32|
	v_max_f32_e64 v20, |v30|, |v30|
	v_max_f32_e32 v19, v20, v19
	v_max_f32_e64 v20, |v33|, |v33|
	v_max_f32_e64 v21, |v31|, |v31|
	v_max_f32_e32 v20, v21, v20
	v_max3_f32 v18, v18, v19, v20
	s_waitcnt lgkmcnt(2)
	v_max_f32_e64 v19, |v82|, |v82|
	v_max_f32_e64 v20, |v80|, |v80|
	v_max_f32_e32 v19, v20, v19
	v_max_f32_e64 v20, |v83|, |v83|
	v_max_f32_e64 v21, |v81|, |v81|
	v_max_f32_e32 v20, v21, v20
	v_max3_f32 v18, v18, v19, v20
	s_waitcnt lgkmcnt(0)
	v_max_f32_e64 v19, |v86|, |v86|
	v_max_f32_e64 v20, |v84|, |v84|
	v_max_f32_e32 v19, v20, v19
	v_max_f32_e64 v20, |v87|, |v87|
	v_max_f32_e64 v21, |v85|, |v85|
	v_max_f32_e32 v20, v21, v20
	v_max3_f32 v18, v18, v19, v20
	v_bfe_u32 v18, v18, 23, 8
	v_max_u32_e32 v34, 3, v18
	v_lshlrev_b32_e32 v18, 23, v34
	v_sub_u32_e32 v61, 0x80000000, v18
	v_mul_f32_e32 v4, v4, v61
	v_med3_f32 v18, v4, s40, v78
	v_mul_f32_e32 v4, v5, v61
	v_mul_f32_e32 v5, v8, v61
	v_med3_f32 v19, v4, s40, v78
	v_mul_f32_e32 v4, v6, v61
	v_med3_f32 v20, v5, s40, v78
	v_mul_f32_e32 v5, v7, v61
	v_mul_f32_e32 v6, v9, v61
	v_mul_f32_e32 v7, v12, v61
	v_mul_f32_e32 v8, v13, v61
	v_mul_f32_e32 v9, v16, v61
	v_med3_f32 v21, v6, s40, v78
	v_mul_f32_e32 v6, v10, v61
	v_med3_f32 v22, v7, s40, v78
	v_mul_f32_e32 v7, v11, v61
	v_med3_f32 v23, v8, s40, v78
	v_mul_f32_e32 v8, v14, v61
	v_med3_f32 v24, v9, s40, v78
	v_mul_f32_e32 v9, v15, v61
	v_mul_f32_e32 v10, v17, v61
	v_mul_f32_e32 v11, v28, v61
	v_mul_f32_e32 v12, v29, v61
	v_mul_f32_e32 v13, v32, v61
	v_mul_f32_e32 v14, v33, v61
	v_mul_f32_e32 v15, v82, v61
	v_mul_f32_e32 v16, v83, v61
	v_mul_f32_e32 v17, v86, v61
	v_mul_f32_e32 v2, v2, v61
	v_mul_f32_e32 v3, v3, v61
	v_med3_f32 v25, v10, s40, v78
	v_mul_f32_e32 v10, v26, v61
	v_med3_f32 v26, v11, s40, v78
	v_mul_f32_e32 v11, v27, v61
	v_med3_f32 v27, v12, s40, v78
	v_mul_f32_e32 v12, v30, v61
	v_med3_f32 v28, v13, s40, v78
	v_mul_f32_e32 v13, v31, v61
	v_med3_f32 v29, v14, s40, v78
	v_mul_f32_e32 v14, v80, v61
	v_med3_f32 v30, v15, s40, v78
	v_mul_f32_e32 v15, v81, v61
	v_med3_f32 v31, v16, s40, v78
	v_mul_f32_e32 v16, v84, v61
	v_med3_f32 v32, v17, s40, v78
	v_mul_f32_e32 v17, v85, v61
	v_mul_f32_e32 v33, v87, v61
	v_med3_f32 v2, v2, s40, v78
	v_med3_f32 v3, v3, s40, v78
	v_med3_f32 v4, v4, s40, v78
	v_med3_f32 v5, v5, s40, v78
	v_med3_f32 v6, v6, s40, v78
	v_med3_f32 v7, v7, s40, v78
	v_med3_f32 v8, v8, s40, v78
	v_med3_f32 v9, v9, s40, v78
	v_med3_f32 v10, v10, s40, v78
	v_med3_f32 v11, v11, s40, v78
	v_med3_f32 v12, v12, s40, v78
	v_med3_f32 v13, v13, s40, v78
	v_med3_f32 v14, v14, s40, v78
	v_med3_f32 v15, v15, s40, v78
	v_med3_f32 v16, v16, s40, v78
	v_med3_f32 v17, v17, s40, v78
	v_med3_f32 v33, v33, s40, v78
	s_and_b32 s7, 0xffff, s7
	v_cvt_scalef32_2xpk16_fp6_f32 v[2:7], v[2:17], v[18:33], 1.0
	v_mov_b32_e32 v32, v6
	v_or_b32_e32 v6, s7, v40
	v_mov_b32_e32 v33, v7
	v_lshlrev_b32_e32 v6, 12, v6
	v_mov_b32_e32 v7, v35
	v_or_b32_e32 v8, s6, v41
	v_lshl_add_u64 v[6:7], s[18:19], 0, v[6:7]
	s_and_b32 s16, s6, 0x1f80
	v_lshrrev_b32_e32 v8, 1, v8
	v_and_b32_e32 v8, 48, v8
	v_mov_b32_e32 v9, v35
	v_lshl_add_u64 v[6:7], v[6:7], 0, s[16:17]
	v_lshl_add_u64 v[6:7], v[6:7], 0, v[8:9]
	v_add_u32_e32 v34, -2, v34
	v_lshl_add_u64 v[144:145], v[6:7], 0, 0
	v_mov_b32_e32 v146, v2
	v_mov_b32_e32 v147, v3
	v_mov_b32_e32 v148, v4
	v_mov_b32_e32 v149, v5
	v_lshl_add_u64 v[150:151], v[6:7], 0, 64
	v_mov_b32_e32 v152, v32
	v_mov_b32_e32 v153, v33
	v_mov_b32_e32 v154, v34
	v_mov_b32_e32 v155, v35
	s_mov_b64 s[74:75], -1
	s_mov_b64 s[76:77], 0
	s_waitcnt lgkmcnt(0)

.LBB0_28:
	s_mov_b32 s62, 0x4000
	s_mov_b32 s66, 0x8000
	s_mov_b32 s67, 0
	v_mad_u32_u24 v142, v38, s21, v44
	v_mad_u64_u32 v[140:141], s[64:65], v4, s62, v[2:3]
	global_load_dword v100, v[140:141], off
	v_lshl_add_u64 v[140:141], v[140:141], 0, s[66:67]
	global_load_dword v101, v[140:141], off
	v_lshl_add_u64 v[140:141], v[140:141], 0, s[66:67]
	global_load_dword v102, v[140:141], off
	v_lshl_add_u64 v[140:141], v[140:141], 0, s[66:67]
	global_load_dword v103, v[140:141], off
	v_lshl_add_u64 v[140:141], v[140:141], 0, s[66:67]
	global_load_dword v104, v[140:141], off
	v_lshl_add_u64 v[140:141], v[140:141], 0, s[66:67]
	global_load_dword v105, v[140:141], off
	v_lshl_add_u64 v[140:141], v[140:141], 0, s[66:67]
	global_load_dword v106, v[140:141], off
	v_lshl_add_u64 v[140:141], v[140:141], 0, s[66:67]
	global_load_dword v107, v[140:141], off
	v_lshl_add_u64 v[140:141], v[140:141], 0, s[66:67]
	global_load_dword v108, v[140:141], off
	v_lshl_add_u64 v[140:141], v[140:141], 0, s[66:67]
	global_load_dword v109, v[140:141], off
	v_lshl_add_u64 v[140:141], v[140:141], 0, s[66:67]
	global_load_dword v110, v[140:141], off
	v_lshl_add_u64 v[140:141], v[140:141], 0, s[66:67]
	global_load_dword v111, v[140:141], off
	v_lshl_add_u64 v[140:141], v[140:141], 0, s[66:67]
	global_load_dword v112, v[140:141], off
	v_lshl_add_u64 v[140:141], v[140:141], 0, s[66:67]
	global_load_dword v113, v[140:141], off
	v_lshl_add_u64 v[140:141], v[140:141], 0, s[66:67]
	global_load_dword v114, v[140:141], off
	v_lshl_add_u64 v[140:141], v[140:141], 0, s[66:67]
	global_load_dword v115, v[140:141], off
	v_lshl_add_u64 v[140:141], v[140:141], 0, s[66:67]
	global_load_dword v116, v[140:141], off
	v_lshl_add_u64 v[140:141], v[140:141], 0, s[66:67]
	global_load_dword v117, v[140:141], off
	v_lshl_add_u64 v[140:141], v[140:141], 0, s[66:67]
	global_load_dword v118, v[140:141], off
	v_lshl_add_u64 v[140:141], v[140:141], 0, s[66:67]
	global_load_dword v119, v[140:141], off
	v_lshl_add_u64 v[140:141], v[140:141], 0, s[66:67]
	global_load_dword v120, v[140:141], off
	v_lshl_add_u64 v[140:141], v[140:141], 0, s[66:67]
	global_load_dword v121, v[140:141], off
	v_lshl_add_u64 v[140:141], v[140:141], 0, s[66:67]
	global_load_dword v122, v[140:141], off
	v_lshl_add_u64 v[140:141], v[140:141], 0, s[66:67]
	global_load_dword v123, v[140:141], off
	v_lshl_add_u64 v[140:141], v[140:141], 0, s[66:67]
	global_load_dword v124, v[140:141], off
	v_lshl_add_u64 v[140:141], v[140:141], 0, s[66:67]
	global_load_dword v125, v[140:141], off
	v_lshl_add_u64 v[140:141], v[140:141], 0, s[66:67]
	global_load_dword v126, v[140:141], off
	v_lshl_add_u64 v[140:141], v[140:141], 0, s[66:67]
	global_load_dword v127, v[140:141], off
	v_lshl_add_u64 v[140:141], v[140:141], 0, s[66:67]
	global_load_dword v128, v[140:141], off
	v_lshl_add_u64 v[140:141], v[140:141], 0, s[66:67]
	global_load_dword v129, v[140:141], off
	v_lshl_add_u64 v[140:141], v[140:141], 0, s[66:67]
	global_load_dword v130, v[140:141], off
	v_lshl_add_u64 v[140:141], v[140:141], 0, s[66:67]
	global_load_dword v131, v[140:141], off
	s_and_saveexec_b64 s[70:71], s[74:75]
	global_store_dwordx4 v[144:145], v[146:149], off
	global_store_dwordx4 v[150:151], v[152:155], off
	s_mov_b64 exec, s[70:71]
	s_and_saveexec_b64 s[70:71], s[76:77]
	global_store_dwordx4 v[156:157], v[158:161], off
	global_store_dwordx4 v[162:163], v[164:167], off
	s_mov_b64 exec, s[70:71]
	s_mov_b64 s[74:75], 0
	s_mov_b64 s[76:77], 0
	s_waitcnt vmcnt(32)
	ds_write_b32 v142, v100
	ds_write_b32 v142, v101 offset:264
	ds_write_b32 v142, v102 offset:528
	ds_write_b32 v142, v103 offset:792
	s_waitcnt vmcnt(28)
	ds_write_b32 v142, v104 offset:1056
	ds_write_b32 v142, v105 offset:1320
	ds_write_b32 v142, v106 offset:1584
	ds_write_b32 v142, v107 offset:1848
	s_waitcnt vmcnt(24)
	ds_write_b32 v142, v108 offset:2112
	ds_write_b32 v142, v109 offset:2376
	ds_write_b32 v142, v110 offset:2640
	ds_write_b32 v142, v111 offset:2904
	s_waitcnt vmcnt(20)
	ds_write_b32 v142, v112 offset:3168
	ds_write_b32 v142, v113 offset:3432
	ds_write_b32 v142, v114 offset:3696
	ds_write_b32 v142, v115 offset:3960
	s_waitcnt vmcnt(16)
	ds_write_b32 v142, v116 offset:4224
	ds_write_b32 v142, v117 offset:4488
	ds_write_b32 v142, v118 offset:4752
	ds_write_b32 v142, v119 offset:5016
	s_waitcnt vmcnt(12)
	ds_write_b32 v142, v120 offset:5280
	ds_write_b32 v142, v121 offset:5544
	ds_write_b32 v142, v122 offset:5808
	ds_write_b32 v142, v123 offset:6072
	s_waitcnt vmcnt(8)
	ds_write_b32 v142, v124 offset:6336
	ds_write_b32 v142, v125 offset:6600
	ds_write_b32 v142, v126 offset:6864
	ds_write_b32 v142, v127 offset:7128
	s_waitcnt vmcnt(4)
	ds_write_b32 v142, v128 offset:7392
	ds_write_b32 v142, v129 offset:7656
	ds_write_b32 v142, v130 offset:7920
	ds_write_b32 v142, v131 offset:8184
	s_waitcnt lgkmcnt(0)
	ds_read2_b32 v[2:3], v63 offset1:33
	v_add_u32_e32 v16, 0x800, v63
	v_add_u32_e32 v18, 0x400, v63
	v_add_u32_e32 v19, 0xc00, v63
	ds_read2_b32 v[4:5], v16 offset0:16 offset1:49
	ds_read2_b32 v[6:7], v63 offset0:66 offset1:99
	ds_read2_b32 v[8:9], v16 offset0:82 offset1:115
	ds_read2_b32 v[10:11], v63 offset0:132 offset1:165
	ds_read2_b32 v[12:13], v16 offset0:148 offset1:181
	ds_read2_b32 v[14:15], v63 offset0:198 offset1:231
	ds_read2_b32 v[16:17], v16 offset0:214 offset1:247
	ds_read2_b32 v[26:27], v18 offset0:8 offset1:41
	ds_read2_b32 v[28:29], v19 offset0:24 offset1:57
	ds_read2_b32 v[30:31], v18 offset0:74 offset1:107
	ds_read2_b32 v[32:33], v19 offset0:90 offset1:123
	ds_read2_b32 v[80:81], v18 offset0:140 offset1:173
	ds_read2_b32 v[82:83], v19 offset0:156 offset1:189
	ds_read2_b32 v[84:85], v18 offset0:206 offset1:239
	ds_read2_b32 v[86:87], v19 offset0:222 offset1:255
	s_waitcnt lgkmcnt(14)
	v_max_f32_e64 v18, |v4|, |v4|
	v_max_f32_e64 v19, |v2|, |v2|
	v_max_f32_e32 v18, v19, v18
	v_max_f32_e64 v19, |v5|, |v5|
	v_max_f32_e64 v20, |v3|, |v3|
	v_max_f32_e32 v19, v20, v19
	v_max3_f32 v18, v18, 0, v19
	s_waitcnt lgkmcnt(12)
	v_max_f32_e64 v19, |v8|, |v8|
	v_max_f32_e64 v20, |v6|, |v6|
	v_max_f32_e32 v19, v20, v19
	v_max_f32_e64 v20, |v9|, |v9|
	v_max_f32_e64 v21, |v7|, |v7|
	v_max_f32_e32 v20, v21, v20
	v_max3_f32 v18, v18, v19, v20
	s_waitcnt lgkmcnt(10)
	v_max_f32_e64 v19, |v12|, |v12|
	v_max_f32_e64 v20, |v10|, |v10|
	v_max_f32_e32 v19, v20, v19
	v_max_f32_e64 v20, |v13|, |v13|
	v_max_f32_e64 v21, |v11|, |v11|
	v_max_f32_e32 v20, v21, v20
	v_max3_f32 v18, v18, v19, v20
	s_waitcnt lgkmcnt(8)
	v_max_f32_e64 v19, |v16|, |v16|
	v_max_f32_e64 v20, |v14|, |v14|
	v_max_f32_e32 v19, v20, v19
	v_max_f32_e64 v20, |v17|, |v17|
	v_max_f32_e64 v21, |v15|, |v15|
	v_max_f32_e32 v20, v21, v20
	v_max3_f32 v18, v18, v19, v20
	s_waitcnt lgkmcnt(6)
	v_max_f32_e64 v19, |v28|, |v28|
	v_max_f32_e64 v20, |v26|, |v26|
	v_max_f32_e32 v19, v20, v19
	v_max_f32_e64 v20, |v29|, |v29|
	v_max_f32_e64 v21, |v27|, |v27|
	v_max_f32_e32 v20, v21, v20
	v_max3_f32 v18, v18, v19, v20
	s_waitcnt lgkmcnt(4)
	v_max_f32_e64 v19, |v32|, |v32|
	v_max_f32_e64 v20, |v30|, |v30|
	v_max_f32_e32 v19, v20, v19
	v_max_f32_e64 v20, |v33|, |v33|
	v_max_f32_e64 v21, |v31|, |v31|
	v_max_f32_e32 v20, v21, v20
	v_max3_f32 v18, v18, v19, v20
	s_waitcnt lgkmcnt(2)
	v_max_f32_e64 v19, |v82|, |v82|
	v_max_f32_e64 v20, |v80|, |v80|
	v_max_f32_e32 v19, v20, v19
	v_max_f32_e64 v20, |v83|, |v83|
	v_max_f32_e64 v21, |v81|, |v81|
	v_max_f32_e32 v20, v21, v20
	v_max3_f32 v18, v18, v19, v20
	s_waitcnt lgkmcnt(0)
	v_max_f32_e64 v19, |v86|, |v86|
	v_max_f32_e64 v20, |v84|, |v84|
	v_max_f32_e32 v19, v20, v19
	v_max_f32_e64 v20, |v87|, |v87|
	v_max_f32_e64 v21, |v85|, |v85|
	v_max_f32_e32 v20, v21, v20
	v_max3_f32 v18, v18, v19, v20
	v_bfe_u32 v18, v18, 23, 8
	v_max_u32_e32 v34, 3, v18
	v_lshlrev_b32_e32 v18, 23, v34
	v_sub_u32_e32 v61, 0x80000000, v18
	v_mul_f32_e32 v4, v4, v61
	v_med3_f32 v18, v4, s40, v78
	v_mul_f32_e32 v4, v5, v61
	v_mul_f32_e32 v5, v8, v61
	v_med3_f32 v19, v4, s40, v78
	v_mul_f32_e32 v4, v6, v61
	v_med3_f32 v20, v5, s40, v78
	v_mul_f32_e32 v5, v7, v61
	v_mul_f32_e32 v6, v9, v61
	v_mul_f32_e32 v7, v12, v61
	v_mul_f32_e32 v8, v13, v61
	v_mul_f32_e32 v9, v16, v61
	v_med3_f32 v21, v6, s40, v78
	v_mul_f32_e32 v6, v10, v61
	v_med3_f32 v22, v7, s40, v78
	v_mul_f32_e32 v7, v11, v61
	v_med3_f32 v23, v8, s40, v78
	v_mul_f32_e32 v8, v14, v61
	v_med3_f32 v24, v9, s40, v78
	v_mul_f32_e32 v9, v15, v61
	v_mul_f32_e32 v10, v17, v61
	v_mul_f32_e32 v11, v28, v61
	v_mul_f32_e32 v12, v29, v61
	v_mul_f32_e32 v13, v32, v61
	v_mul_f32_e32 v14, v33, v61
	v_mul_f32_e32 v15, v82, v61
	v_mul_f32_e32 v16, v83, v61
	v_mul_f32_e32 v17, v86, v61
	v_mul_f32_e32 v2, v2, v61
	v_mul_f32_e32 v3, v3, v61
	v_med3_f32 v25, v10, s40, v78
	v_mul_f32_e32 v10, v26, v61
	v_med3_f32 v26, v11, s40, v78
	v_mul_f32_e32 v11, v27, v61
	v_med3_f32 v27, v12, s40, v78
	v_mul_f32_e32 v12, v30, v61
	v_med3_f32 v28, v13, s40, v78
	v_mul_f32_e32 v13, v31, v61
	v_med3_f32 v29, v14, s40, v78
	v_mul_f32_e32 v14, v80, v61
	v_med3_f32 v30, v15, s40, v78
	v_mul_f32_e32 v15, v81, v61
	v_med3_f32 v31, v16, s40, v78
	v_mul_f32_e32 v16, v84, v61
	v_med3_f32 v32, v17, s40, v78
	v_mul_f32_e32 v17, v85, v61
	v_mul_f32_e32 v33, v87, v61
	v_med3_f32 v2, v2, s40, v78
	v_med3_f32 v3, v3, s40, v78
	v_med3_f32 v4, v4, s40, v78
	v_med3_f32 v5, v5, s40, v78
	v_med3_f32 v6, v6, s40, v78
	v_med3_f32 v7, v7, s40, v78
	v_med3_f32 v8, v8, s40, v78
	v_med3_f32 v9, v9, s40, v78
	v_med3_f32 v10, v10, s40, v78
	v_med3_f32 v11, v11, s40, v78
	v_med3_f32 v12, v12, s40, v78
	v_med3_f32 v13, v13, s40, v78
	v_med3_f32 v14, v14, s40, v78
	v_med3_f32 v15, v15, s40, v78
	v_med3_f32 v16, v16, s40, v78
	v_med3_f32 v17, v17, s40, v78
	v_med3_f32 v33, v33, s40, v78
	s_and_b32 s11, 0xffff, s11
	v_cvt_scalef32_2xpk16_fp6_f32 v[2:7], v[2:17], v[18:33], 1.0
	v_mov_b32_e32 v32, v6
	v_or_b32_e32 v6, s11, v40
	v_mov_b32_e32 v33, v7
	v_mul_u32_u24_e32 v6, 0x1800, v6
	v_mov_b32_e32 v7, v35
	v_or_b32_e32 v8, s9, v41
	v_lshl_add_u64 v[6:7], s[14:15], 0, v[6:7]
	s_and_b32 s16, s8, 0x7f80
	v_lshrrev_b32_e32 v8, 1, v8
	v_and_b32_e32 v8, 48, v8
	v_mov_b32_e32 v9, v35
	v_lshl_add_u64 v[6:7], v[6:7], 0, s[16:17]
	v_lshl_add_u64 v[6:7], v[6:7], 0, v[8:9]
	v_lshl_add_u64 v[8:9], v[6:7], 0, s[22:23]
	v_add_co_u32_e32 v6, vcc, 0x800000, v6
	v_add_u32_e32 v34, -2, v34
	s_nop 0
	v_addc_co_u32_e32 v7, vcc, 0, v7, vcc
	v_lshl_add_u64 v[144:145], v[6:7], 0, s[72:73]
	v_mov_b32_e32 v146, v2
	v_mov_b32_e32 v147, v3
	v_mov_b32_e32 v148, v4
	v_mov_b32_e32 v149, v5
	v_lshl_add_u64 v[150:151], v[8:9], 0, 64
	v_mov_b32_e32 v152, v32
	v_mov_b32_e32 v153, v33
	v_mov_b32_e32 v154, v34
	v_mov_b32_e32 v155, v35
	s_mov_b64 s[74:75], -1
	s_mov_b64 s[76:77], 0
	s_waitcnt lgkmcnt(0)
	s_mov_b64 s[8:9], 0

.LBB0_32:
	s_mov_b32 s62, 0x4000
	s_mov_b32 s66, 0x8000
	s_mov_b32 s67, 0
	v_mad_u32_u24 v142, v38, s21, v44
	v_mad_u64_u32 v[140:141], s[64:65], v4, s62, v[2:3]
	global_load_dword v100, v[140:141], off
	v_lshl_add_u64 v[140:141], v[140:141], 0, s[66:67]
	global_load_dword v101, v[140:141], off
	v_lshl_add_u64 v[140:141], v[140:141], 0, s[66:67]
	global_load_dword v102, v[140:141], off
	v_lshl_add_u64 v[140:141], v[140:141], 0, s[66:67]
	global_load_dword v103, v[140:141], off
	v_lshl_add_u64 v[140:141], v[140:141], 0, s[66:67]
	global_load_dword v104, v[140:141], off
	v_lshl_add_u64 v[140:141], v[140:141], 0, s[66:67]
	global_load_dword v105, v[140:141], off
	v_lshl_add_u64 v[140:141], v[140:141], 0, s[66:67]
	global_load_dword v106, v[140:141], off
	v_lshl_add_u64 v[140:141], v[140:141], 0, s[66:67]
	global_load_dword v107, v[140:141], off
	v_lshl_add_u64 v[140:141], v[140:141], 0, s[66:67]
	global_load_dword v108, v[140:141], off
	v_lshl_add_u64 v[140:141], v[140:141], 0, s[66:67]
	global_load_dword v109, v[140:141], off
	v_lshl_add_u64 v[140:141], v[140:141], 0, s[66:67]
	global_load_dword v110, v[140:141], off
	v_lshl_add_u64 v[140:141], v[140:141], 0, s[66:67]
	global_load_dword v111, v[140:141], off
	v_lshl_add_u64 v[140:141], v[140:141], 0, s[66:67]
	global_load_dword v112, v[140:141], off
	v_lshl_add_u64 v[140:141], v[140:141], 0, s[66:67]
	global_load_dword v113, v[140:141], off
	v_lshl_add_u64 v[140:141], v[140:141], 0, s[66:67]
	global_load_dword v114, v[140:141], off
	v_lshl_add_u64 v[140:141], v[140:141], 0, s[66:67]
	global_load_dword v115, v[140:141], off
	v_lshl_add_u64 v[140:141], v[140:141], 0, s[66:67]
	global_load_dword v116, v[140:141], off
	v_lshl_add_u64 v[140:141], v[140:141], 0, s[66:67]
	global_load_dword v117, v[140:141], off
	v_lshl_add_u64 v[140:141], v[140:141], 0, s[66:67]
	global_load_dword v118, v[140:141], off
	v_lshl_add_u64 v[140:141], v[140:141], 0, s[66:67]
	global_load_dword v119, v[140:141], off
	v_lshl_add_u64 v[140:141], v[140:141], 0, s[66:67]
	global_load_dword v120, v[140:141], off
	v_lshl_add_u64 v[140:141], v[140:141], 0, s[66:67]
	global_load_dword v121, v[140:141], off
	v_lshl_add_u64 v[140:141], v[140:141], 0, s[66:67]
	global_load_dword v122, v[140:141], off
	v_lshl_add_u64 v[140:141], v[140:141], 0, s[66:67]
	global_load_dword v123, v[140:141], off
	v_lshl_add_u64 v[140:141], v[140:141], 0, s[66:67]
	global_load_dword v124, v[140:141], off
	v_lshl_add_u64 v[140:141], v[140:141], 0, s[66:67]
	global_load_dword v125, v[140:141], off
	v_lshl_add_u64 v[140:141], v[140:141], 0, s[66:67]
	global_load_dword v126, v[140:141], off
	v_lshl_add_u64 v[140:141], v[140:141], 0, s[66:67]
	global_load_dword v127, v[140:141], off
	v_lshl_add_u64 v[140:141], v[140:141], 0, s[66:67]
	global_load_dword v128, v[140:141], off
	v_lshl_add_u64 v[140:141], v[140:141], 0, s[66:67]
	global_load_dword v129, v[140:141], off
	v_lshl_add_u64 v[140:141], v[140:141], 0, s[66:67]
	global_load_dword v130, v[140:141], off
	v_lshl_add_u64 v[140:141], v[140:141], 0, s[66:67]
	global_load_dword v131, v[140:141], off
	s_and_saveexec_b64 s[70:71], s[74:75]
	global_store_dwordx4 v[144:145], v[146:149], off
	global_store_dwordx4 v[150:151], v[152:155], off
	s_mov_b64 exec, s[70:71]
	s_and_saveexec_b64 s[70:71], s[76:77]
	global_store_dwordx4 v[156:157], v[158:161], off
	global_store_dwordx4 v[162:163], v[164:167], off
	s_mov_b64 exec, s[70:71]
	s_mov_b64 s[74:75], 0
	s_mov_b64 s[76:77], 0
	s_waitcnt vmcnt(32)
	ds_write_b32 v142, v100
	ds_write_b32 v142, v101 offset:264
	ds_write_b32 v142, v102 offset:528
	ds_write_b32 v142, v103 offset:792
	s_waitcnt vmcnt(28)
	ds_write_b32 v142, v104 offset:1056
	ds_write_b32 v142, v105 offset:1320
	ds_write_b32 v142, v106 offset:1584
	ds_write_b32 v142, v107 offset:1848
	s_waitcnt vmcnt(24)
	ds_write_b32 v142, v108 offset:2112
	ds_write_b32 v142, v109 offset:2376
	ds_write_b32 v142, v110 offset:2640
	ds_write_b32 v142, v111 offset:2904
	s_waitcnt vmcnt(20)
	ds_write_b32 v142, v112 offset:3168
	ds_write_b32 v142, v113 offset:3432
	ds_write_b32 v142, v114 offset:3696
	ds_write_b32 v142, v115 offset:3960
	s_waitcnt vmcnt(16)
	ds_write_b32 v142, v116 offset:4224
	ds_write_b32 v142, v117 offset:4488
	ds_write_b32 v142, v118 offset:4752
	ds_write_b32 v142, v119 offset:5016
	s_waitcnt vmcnt(12)
	ds_write_b32 v142, v120 offset:5280
	ds_write_b32 v142, v121 offset:5544
	ds_write_b32 v142, v122 offset:5808
	ds_write_b32 v142, v123 offset:6072
	s_waitcnt vmcnt(8)
	ds_write_b32 v142, v124 offset:6336
	ds_write_b32 v142, v125 offset:6600
	ds_write_b32 v142, v126 offset:6864
	ds_write_b32 v142, v127 offset:7128
	s_waitcnt vmcnt(4)
	ds_write_b32 v142, v128 offset:7392
	ds_write_b32 v142, v129 offset:7656
	ds_write_b32 v142, v130 offset:7920
	ds_write_b32 v142, v131 offset:8184
	s_waitcnt lgkmcnt(0)
	ds_read2_b32 v[6:7], v65 offset1:8
	ds_read2_b32 v[10:11], v65 offset0:33 offset1:41
	ds_read2_b32 v[12:13], v65 offset0:66 offset1:74
	ds_read2_b32 v[14:15], v65 offset0:99 offset1:107
	ds_read2_b32 v[16:17], v65 offset0:132 offset1:140
	ds_read2_b32 v[18:19], v65 offset0:165 offset1:173
	s_waitcnt lgkmcnt(5)
	v_bfe_u32 v2, v6, 16, 1
	v_add3_u32 v2, v6, v2, s41
	s_waitcnt lgkmcnt(4)
	v_bfe_u32 v3, v10, 16, 1
	v_lshrrev_b32_e32 v2, 16, v2
	v_add3_u32 v3, v10, v3, s41
	v_and_or_b32 v2, v3, s42, v2
	s_waitcnt lgkmcnt(3)
	v_bfe_u32 v3, v12, 16, 1
	v_add3_u32 v3, v12, v3, s41
	s_waitcnt lgkmcnt(2)
	v_bfe_u32 v4, v14, 16, 1
	ds_read2_b32 v[20:21], v65 offset0:198 offset1:206
	v_lshrrev_b32_e32 v3, 16, v3
	v_add3_u32 v4, v14, v4, s41
	ds_read2_b32 v[22:23], v65 offset0:231 offset1:239
	v_and_or_b32 v3, v4, s42, v3
	s_waitcnt lgkmcnt(3)
	v_bfe_u32 v4, v16, 16, 1
	v_add3_u32 v4, v16, v4, s41
	s_waitcnt lgkmcnt(2)
	v_bfe_u32 v5, v18, 16, 1
	v_lshrrev_b32_e32 v4, 16, v4
	v_add3_u32 v5, v18, v5, s41
	v_and_or_b32 v4, v5, s42, v4
	s_waitcnt lgkmcnt(1)
	v_bfe_u32 v5, v20, 16, 1
	v_add3_u32 v5, v20, v5, s41
	s_waitcnt lgkmcnt(0)
	v_bfe_u32 v6, v22, 16, 1
	v_lshrrev_b32_e32 v5, 16, v5
	v_add3_u32 v6, v22, v6, s41
	v_and_or_b32 v5, v6, s42, v5
	v_or_b32_e32 v6, s8, v64
	s_lshl_b32 s16, s9, 1
	v_mul_u32_u24_e32 v6, 0xc00, v6
	v_lshl_add_u64 v[8:9], v[48:49], 0, s[16:17]
	v_lshlrev_b32_e32 v34, 1, v6
	v_lshl_add_u64 v[24:25], v[8:9], 0, v[34:35]
	v_lshl_add_u64 v[144:145], v[24:25], 0, 0
	v_mov_b32_e32 v146, v2
	v_mov_b32_e32 v147, v3
	v_mov_b32_e32 v148, v4
	v_mov_b32_e32 v149, v5
	v_bfe_u32 v6, v23, 16, 1
	v_add3_u32 v6, v23, v6, s41
	v_bfe_u32 v2, v7, 16, 1
	v_add3_u32 v2, v7, v2, s41
	v_bfe_u32 v3, v11, 16, 1
	v_lshrrev_b32_e32 v2, 16, v2
	v_add3_u32 v3, v11, v3, s41
	v_and_or_b32 v2, v3, s42, v2
	v_bfe_u32 v3, v13, 16, 1
	v_add3_u32 v3, v13, v3, s41
	v_bfe_u32 v4, v15, 16, 1
	v_lshrrev_b32_e32 v3, 16, v3
	v_add3_u32 v4, v15, v4, s41
	v_and_or_b32 v3, v4, s42, v3
	v_bfe_u32 v4, v17, 16, 1
	v_add3_u32 v4, v17, v4, s41
	v_bfe_u32 v5, v19, 16, 1
	v_lshrrev_b32_e32 v4, 16, v4
	v_add3_u32 v5, v19, v5, s41
	v_and_or_b32 v4, v5, s42, v4
	v_bfe_u32 v5, v21, 16, 1
	v_add3_u32 v5, v21, v5, s41
	v_lshrrev_b32_e32 v5, 16, v5
	v_and_or_b32 v5, v6, s42, v5
	v_or_b32_e32 v6, s8, v66
	v_mul_u32_u24_e32 v10, 0xc00, v6
	v_lshlrev_b32_e32 v34, 1, v10
	ds_read2_b32 v[6:7], v65 offset0:16 offset1:24
	v_lshl_add_u64 v[10:11], v[8:9], 0, v[34:35]
	v_lshl_add_u64 v[150:151], v[10:11], 0, 0
	v_mov_b32_e32 v152, v2
	v_mov_b32_e32 v153, v3
	v_mov_b32_e32 v154, v4
	v_mov_b32_e32 v155, v5
	ds_read2_b32 v[10:11], v65 offset0:49 offset1:57
	ds_read2_b32 v[12:13], v65 offset0:82 offset1:90
	ds_read2_b32 v[14:15], v65 offset0:115 offset1:123
	s_waitcnt lgkmcnt(3)
	v_bfe_u32 v2, v6, 16, 1
	v_add3_u32 v2, v6, v2, s41
	s_waitcnt lgkmcnt(2)
	v_bfe_u32 v3, v10, 16, 1
	ds_read2_b32 v[16:17], v65 offset0:148 offset1:156
	v_lshrrev_b32_e32 v2, 16, v2
	v_add3_u32 v3, v10, v3, s41
	ds_read2_b32 v[18:19], v65 offset0:181 offset1:189
	v_and_or_b32 v2, v3, s42, v2
	s_waitcnt lgkmcnt(3)
	v_bfe_u32 v3, v12, 16, 1
	v_add3_u32 v3, v12, v3, s41
	s_waitcnt lgkmcnt(2)
	v_bfe_u32 v4, v14, 16, 1
	ds_read2_b32 v[20:21], v65 offset0:214 offset1:222
	v_lshrrev_b32_e32 v3, 16, v3
	v_add3_u32 v4, v14, v4, s41
	ds_read2_b32 v[22:23], v65 offset0:247 offset1:255
	v_and_or_b32 v3, v4, s42, v3
	s_waitcnt lgkmcnt(3)
	v_bfe_u32 v4, v16, 16, 1
	v_add3_u32 v4, v16, v4, s41
	s_waitcnt lgkmcnt(2)
	v_bfe_u32 v5, v18, 16, 1
	v_lshrrev_b32_e32 v4, 16, v4
	v_add3_u32 v5, v18, v5, s41
	v_and_or_b32 v4, v5, s42, v4
	s_waitcnt lgkmcnt(1)
	v_bfe_u32 v5, v20, 16, 1
	v_add3_u32 v5, v20, v5, s41
	s_waitcnt lgkmcnt(0)
	v_bfe_u32 v6, v22, 16, 1
	v_lshrrev_b32_e32 v5, 16, v5
	v_add3_u32 v6, v22, v6, s41
	v_and_or_b32 v5, v6, s42, v5
	v_or_b32_e32 v6, s8, v67
	v_mul_u32_u24_e32 v6, 0xc00, v6
	v_lshlrev_b32_e32 v34, 1, v6
	v_lshl_add_u64 v[24:25], v[8:9], 0, v[34:35]
	v_lshl_add_u64 v[156:157], v[24:25], 0, 0
	v_mov_b32_e32 v158, v2
	v_mov_b32_e32 v159, v3
	v_mov_b32_e32 v160, v4
	v_mov_b32_e32 v161, v5
	v_bfe_u32 v6, v23, 16, 1
	v_add3_u32 v6, v23, v6, s41
	v_bfe_u32 v2, v7, 16, 1
	v_add3_u32 v2, v7, v2, s41
	v_bfe_u32 v3, v11, 16, 1
	v_lshrrev_b32_e32 v2, 16, v2
	v_add3_u32 v3, v11, v3, s41
	v_and_or_b32 v2, v3, s42, v2
	v_bfe_u32 v3, v13, 16, 1
	v_add3_u32 v3, v13, v3, s41
	v_bfe_u32 v4, v15, 16, 1
	v_lshrrev_b32_e32 v3, 16, v3
	v_add3_u32 v4, v15, v4, s41
	v_and_or_b32 v3, v4, s42, v3
	v_bfe_u32 v4, v17, 16, 1
	v_add3_u32 v4, v17, v4, s41
	v_bfe_u32 v5, v19, 16, 1
	v_lshrrev_b32_e32 v4, 16, v4
	v_add3_u32 v5, v19, v5, s41
	v_and_or_b32 v4, v5, s42, v4
	v_bfe_u32 v5, v21, 16, 1
	v_add3_u32 v5, v21, v5, s41
	v_lshrrev_b32_e32 v5, 16, v5
	v_and_or_b32 v5, v6, s42, v5
	v_or_b32_e32 v6, s8, v68
	v_mul_u32_u24_e32 v6, 0xc00, v6
	v_lshlrev_b32_e32 v34, 1, v6
	v_lshl_add_u64 v[6:7], v[8:9], 0, v[34:35]
	v_lshl_add_u64 v[162:163], v[6:7], 0, 0
	v_mov_b32_e32 v164, v2
	v_mov_b32_e32 v165, v3
	v_mov_b32_e32 v166, v4
	v_mov_b32_e32 v167, v5
	s_mov_b64 s[74:75], -1
	s_mov_b64 s[76:77], -1
	s_waitcnt lgkmcnt(0)

.LBB0_35:
	s_andn2_b64 vcc, exec, s[6:7]
	s_cbranch_vccnz .LBB0_55
	s_bfe_u32 s7, s38, 0x90007
	s_lshl_b32 s8, s7, 6
	v_or_b32_e32 v2, s8, v70
	v_or_b32_e32 v6, s8, v71
	v_or_b32_e32 v8, s8, v72
	v_or_b32_e32 v10, s8, v73
	v_or_b32_e32 v12, s8, v74
	v_or_b32_e32 v14, s8, v75
	v_or_b32_e32 v16, s8, v76
	v_or_b32_e32 v20, s8, v38
	s_waitcnt lgkmcnt(0)
	s_load_dwordx4 s[8:11], s[12:13], 0xa0
	s_lshl_b32 s6, s25, 2
	s_and_b32 s6, s6, 0x3f80
	v_lshl_or_b32 v4, v2, 14, s6
	v_mov_b32_e32 v5, v35
	v_lshl_or_b32 v6, v6, 14, s6
	v_mov_b32_e32 v7, v35
	v_lshl_or_b32 v8, v8, 14, s6
	v_mov_b32_e32 v9, v35
	v_lshl_or_b32 v10, v10, 14, s6
	v_mov_b32_e32 v11, v35
	v_lshl_or_b32 v12, v12, 14, s6
	v_mov_b32_e32 v13, v35
	v_lshl_or_b32 v14, v14, 14, s6
	v_mov_b32_e32 v15, v35
	v_lshl_or_b32 v16, v16, 14, s6
	v_mov_b32_e32 v17, v35
	v_lshl_or_b32 v18, v20, 14, s6
	v_mov_b32_e32 v19, v35
	v_lshlrev_b32_e32 v34, 2, v20
	s_waitcnt lgkmcnt(0)
	s_cmp_lg_u64 s[8:9], 0
	v_lshl_add_u64 v[20:21], s[10:11], 0, v[42:43]
	v_lshl_or_b32 v2, s7, 8, v58
	v_mov_b32_e32 v3, v37
	s_mov_b64 s[26:27], 0
	s_cselect_b64 s[36:37], -1, 0
	v_lshl_add_u64 v[4:5], v[20:21], 0, v[4:5]
	v_lshl_add_u64 v[6:7], v[20:21], 0, v[6:7]
	v_lshl_add_u64 v[8:9], v[20:21], 0, v[8:9]
	v_lshl_add_u64 v[10:11], v[20:21], 0, v[10:11]
	v_lshl_add_u64 v[12:13], v[20:21], 0, v[12:13]
	v_lshl_add_u64 v[14:15], v[20:21], 0, v[14:15]
	v_lshl_add_u64 v[16:17], v[20:21], 0, v[16:17]
	v_lshl_add_u64 v[18:19], v[20:21], 0, v[18:19]
	v_mov_b32_e32 v22, v69
	s_and_saveexec_b64 s[70:71], s[74:75]
	global_store_dwordx4 v[144:145], v[146:149], off
	global_store_dwordx4 v[150:151], v[152:155], off
	s_mov_b64 exec, s[70:71]
	s_and_saveexec_b64 s[70:71], s[76:77]
	global_store_dwordx4 v[156:157], v[158:161], off
	global_store_dwordx4 v[162:163], v[164:167], off
	s_mov_b64 exec, s[70:71]
	s_mov_b64 s[74:75], 0
	s_mov_b64 s[76:77], 0
	s_branch .LBB0_38

.LBB0_54:
	s_waitcnt lgkmcnt(0)
	ds_read2_b32 v[6:7], v59 offset1:16
	ds_read2_b32 v[8:9], v59 offset0:33 offset1:49
	ds_read2_b32 v[10:11], v59 offset0:66 offset1:82
	ds_read2_b32 v[12:13], v59 offset0:99 offset1:115
	ds_read2_b32 v[16:17], v59 offset0:132 offset1:148
	ds_read2_b32 v[18:19], v59 offset0:165 offset1:181
	ds_read2_b32 v[20:21], v59 offset0:198 offset1:214
	ds_read2_b32 v[22:23], v59 offset0:231 offset1:247
	s_waitcnt lgkmcnt(7)
	v_max_f32_e32 v2, v6, v6
	s_waitcnt lgkmcnt(6)
	v_max_f32_e32 v3, v8, v8
	v_med3_f32 v6, v2, s39, v77
	v_med3_f32 v3, v3, s39, v77
	v_mov_b32_e32 v2, v35
	v_cvt_pk_fp8_f32 v2, v6, v3
	s_waitcnt lgkmcnt(5)
	v_max_f32_e32 v4, v10, v10
	s_waitcnt lgkmcnt(4)
	v_max_f32_e32 v5, v12, v12
	v_med3_f32 v4, v4, s39, v77
	v_med3_f32 v5, v5, s39, v77
	v_cvt_pk_fp8_f32 v2, v4, v5 op_sel:[0,0,1]
	s_waitcnt lgkmcnt(3)
	v_max_f32_e32 v3, v16, v16
	s_waitcnt lgkmcnt(2)
	v_max_f32_e32 v4, v18, v18
	v_med3_f32 v8, v3, s39, v77
	v_med3_f32 v4, v4, s39, v77
	v_mov_b32_e32 v3, v35
	v_cvt_pk_fp8_f32 v3, v8, v4
	v_add_u32_e32 v8, 0x400, v59
	ds_read2_b32 v[24:25], v8 offset0:8 offset1:24
	ds_read2_b32 v[26:27], v8 offset0:41 offset1:57
	ds_read2_b32 v[28:29], v8 offset0:74 offset1:90
	ds_read2_b32 v[30:31], v8 offset0:107 offset1:123
	s_waitcnt lgkmcnt(5)
	v_max_f32_e32 v5, v20, v20
	s_waitcnt lgkmcnt(4)
	v_max_f32_e32 v6, v22, v22
	v_med3_f32 v5, v5, s39, v77
	v_med3_f32 v6, v6, s39, v77
	v_cvt_pk_fp8_f32 v3, v5, v6 op_sel:[0,0,1]
	s_waitcnt lgkmcnt(3)
	v_max_f32_e32 v4, v24, v24
	s_waitcnt lgkmcnt(2)
	v_max_f32_e32 v5, v26, v26
	v_med3_f32 v12, v4, s39, v77
	v_med3_f32 v5, v5, s39, v77
	v_mov_b32_e32 v4, v35
	v_cvt_pk_fp8_f32 v4, v12, v5
	ds_read2_b32 v[32:33], v8 offset0:140 offset1:156
	ds_read2_b32 v[80:81], v8 offset0:173 offset1:189
	ds_read2_b32 v[82:83], v8 offset0:206 offset1:222
	s_waitcnt lgkmcnt(4)
	v_max_f32_e32 v6, v28, v28
	s_waitcnt lgkmcnt(3)
	v_max_f32_e32 v10, v30, v30
	v_med3_f32 v6, v6, s39, v77
	v_med3_f32 v5, v10, s39, v77
	ds_read2_b32 v[84:85], v8 offset0:239 offset1:255
	v_cvt_pk_fp8_f32 v4, v6, v5 op_sel:[0,0,1]
	s_waitcnt lgkmcnt(3)
	v_max_f32_e32 v5, v32, v32
	s_waitcnt lgkmcnt(2)
	v_max_f32_e32 v6, v80, v80
	v_med3_f32 v8, v5, s39, v77
	v_med3_f32 v6, v6, s39, v77
	v_mov_b32_e32 v5, v35
	v_cvt_pk_fp8_f32 v5, v8, v6
	s_add_i32 s6, s4, 0xbd80
	s_lshr_b32 s6, s6, 1
	s_waitcnt lgkmcnt(1)
	v_max_f32_e32 v10, v82, v82
	s_waitcnt lgkmcnt(0)
	v_max_f32_e32 v6, v84, v84
	s_and_b32 s16, s6, 0x7fc0
	s_lshl_b32 s6, s4, 5
	v_med3_f32 v8, v10, s39, v77
	v_med3_f32 v6, v6, s39, v77
	s_and_b32 s6, s6, 0xfe0
	v_cvt_pk_fp8_f32 v5, v8, v6 op_sel:[0,0,1]
	v_or_b32_e32 v6, s6, v45
	v_lshl_add_u64 v[14:15], v[50:51], 0, s[16:17]
	v_lshlrev_b32_e32 v34, 9, v6
	v_lshl_add_u64 v[86:87], v[14:15], 0, v[34:35]
	v_lshl_add_u64 v[144:145], v[86:87], 0, 0
	v_mov_b32_e32 v146, v2
	v_mov_b32_e32 v147, v3
	v_mov_b32_e32 v148, v4
	v_mov_b32_e32 v149, v5
	s_nop 1
	v_max_f32_e32 v2, v7, v7
	v_max_f32_e32 v3, v9, v9
	v_med3_f32 v5, v2, s39, v77
	v_med3_f32 v3, v3, s39, v77
	v_mov_b32_e32 v2, v35
	v_cvt_pk_fp8_f32 v2, v5, v3
	v_max_f32_e32 v4, v11, v11
	v_max_f32_e32 v3, v13, v13
	v_med3_f32 v4, v4, s39, v77
	v_med3_f32 v3, v3, s39, v77
	v_cvt_pk_fp8_f32 v2, v4, v3 op_sel:[0,0,1]
	v_max_f32_e32 v3, v17, v17
	v_max_f32_e32 v4, v19, v19
	v_med3_f32 v6, v3, s39, v77
	v_med3_f32 v4, v4, s39, v77
	v_mov_b32_e32 v3, v35
	v_cvt_pk_fp8_f32 v3, v6, v4
	v_max_f32_e32 v5, v21, v21
	v_max_f32_e32 v4, v23, v23
	v_med3_f32 v5, v5, s39, v77
	v_med3_f32 v4, v4, s39, v77
	v_cvt_pk_fp8_f32 v3, v5, v4 op_sel:[0,0,1]
	v_max_f32_e32 v4, v25, v25
	v_max_f32_e32 v5, v27, v27
	v_med3_f32 v7, v4, s39, v77
	v_med3_f32 v5, v5, s39, v77
	v_mov_b32_e32 v4, v35
	v_cvt_pk_fp8_f32 v4, v7, v5
	v_max_f32_e32 v6, v29, v29
	v_max_f32_e32 v5, v31, v31
	v_med3_f32 v6, v6, s39, v77
	v_med3_f32 v5, v5, s39, v77
	v_cvt_pk_fp8_f32 v4, v6, v5 op_sel:[0,0,1]
	v_max_f32_e32 v5, v33, v33
	v_max_f32_e32 v6, v81, v81
	v_med3_f32 v8, v5, s39, v77
	v_med3_f32 v6, v6, s39, v77
	v_mov_b32_e32 v5, v35
	v_cvt_pk_fp8_f32 v5, v8, v6
	v_max_f32_e32 v7, v83, v83
	v_max_f32_e32 v6, v85, v85
	v_med3_f32 v7, v7, s39, v77
	v_med3_f32 v6, v6, s39, v77
	v_cvt_pk_fp8_f32 v5, v7, v6 op_sel:[0,0,1]
	v_or_b32_e32 v6, s6, v62
	v_lshlrev_b32_e32 v34, 9, v6
	v_lshl_add_u64 v[6:7], v[14:15], 0, v[34:35]
	v_lshl_add_u64 v[150:151], v[6:7], 0, 0
	v_mov_b32_e32 v152, v2
	v_mov_b32_e32 v153, v3
	v_mov_b32_e32 v154, v4
	v_mov_b32_e32 v155, v5
	s_mov_b64 s[74:75], -1
	s_mov_b64 s[76:77], 0
	s_waitcnt lgkmcnt(0)

.LBB0_56:
	s_andn2_b64 vcc, exec, s[6:7]
	s_cbranch_vccnz .LBB0_76
	s_add_i32 s6, s4, 0xc380
	s_and_b32 s7, s6, 0xffff
	s_waitcnt lgkmcnt(0)
	s_load_dwordx4 s[8:11], s[12:13], 0x90
	s_mul_i32 s16, s7, 0xaaab
	s_lshr_b32 s26, s16, 16
	s_lshr_b32 s16, s16, 22
	s_mulk_i32 s16, 0x60
	s_sub_i32 s6, s6, s16
	s_and_b32 s47, s26, 0xffc0
	s_lshl_b32 s49, s6, 5
	s_waitcnt lgkmcnt(0)
	s_cmp_lg_u64 s[8:9], 0
	s_cselect_b64 s[36:37], -1, 0
	s_lshl_b32 s6, s6, 7
	v_or_b32_e32 v2, s47, v70
	s_and_b32 s16, s6, 0x3ff80
	v_mul_u32_u24_e32 v34, 0x3000, v2
	v_or_b32_e32 v6, s47, v71
	v_lshl_add_u64 v[2:3], s[16:17], 0, v[34:35]
	v_mul_u32_u24_e32 v34, 0x3000, v6
	v_or_b32_e32 v8, s47, v72
	v_lshl_add_u64 v[6:7], s[16:17], 0, v[34:35]
	v_mul_u32_u24_e32 v34, 0x3000, v8
	v_or_b32_e32 v10, s47, v73
	v_lshl_add_u64 v[8:9], s[16:17], 0, v[34:35]
	v_mul_u32_u24_e32 v34, 0x3000, v10
	v_or_b32_e32 v12, s47, v74
	v_lshl_add_u64 v[10:11], s[16:17], 0, v[34:35]
	v_mul_u32_u24_e32 v34, 0x3000, v12
	v_or_b32_e32 v14, s47, v75
	v_lshl_add_u64 v[12:13], s[16:17], 0, v[34:35]
	v_mul_u32_u24_e32 v34, 0x3000, v14
	v_or_b32_e32 v16, s47, v76
	s_mul_hi_u32 s6, s7, 0x2aaaaab
	v_lshl_add_u64 v[14:15], s[16:17], 0, v[34:35]
	v_mul_u32_u24_e32 v34, 0x3000, v16
	v_or_b32_e32 v22, s47, v38
	v_mov_b64_e32 v[20:21], s[16:17]
	v_lshl_add_u64 v[18:19], s[10:11], 0, v[42:43]
	v_lshl_or_b32 v4, s6, 8, v58
	v_lshl_add_u64 v[16:17], s[16:17], 0, v[34:35]
	v_mad_u64_u32 v[20:21], s[6:7], v22, s43, v[20:21]
	s_mov_b64 s[26:27], 0
	v_lshl_add_u64 v[2:3], v[18:19], 0, v[2:3]
	v_mov_b32_e32 v5, v37
	v_lshl_add_u64 v[6:7], v[18:19], 0, v[6:7]
	v_lshl_add_u64 v[8:9], v[18:19], 0, v[8:9]
	v_lshl_add_u64 v[10:11], v[18:19], 0, v[10:11]
	v_lshl_add_u64 v[12:13], v[18:19], 0, v[12:13]
	v_lshl_add_u64 v[14:15], v[18:19], 0, v[14:15]
	v_lshl_add_u64 v[16:17], v[18:19], 0, v[16:17]
	v_lshl_add_u64 v[18:19], v[18:19], 0, v[20:21]
	v_lshlrev_b32_e32 v34, 2, v22
	v_mov_b32_e32 v22, v69
	s_and_saveexec_b64 s[70:71], s[74:75]
	global_store_dwordx4 v[144:145], v[146:149], off
	global_store_dwordx4 v[150:151], v[152:155], off
	s_mov_b64 exec, s[70:71]
	s_and_saveexec_b64 s[70:71], s[76:77]
	global_store_dwordx4 v[156:157], v[158:161], off
	global_store_dwordx4 v[162:163], v[164:167], off
	s_mov_b64 exec, s[70:71]
	s_mov_b64 s[74:75], 0
	s_mov_b64 s[76:77], 0
	s_branch .LBB0_59

.LBB0_75:
	s_waitcnt lgkmcnt(0)
	ds_read2_b32 v[6:7], v59 offset1:16
	ds_read2_b32 v[8:9], v59 offset0:33 offset1:49
	ds_read2_b32 v[10:11], v59 offset0:66 offset1:82
	ds_read2_b32 v[12:13], v59 offset0:99 offset1:115
	ds_read2_b32 v[16:17], v59 offset0:132 offset1:148
	ds_read2_b32 v[18:19], v59 offset0:165 offset1:181
	ds_read2_b32 v[20:21], v59 offset0:198 offset1:214
	ds_read2_b32 v[22:23], v59 offset0:231 offset1:247
	s_waitcnt lgkmcnt(7)
	v_max_f32_e32 v2, v6, v6
	s_waitcnt lgkmcnt(6)
	v_max_f32_e32 v3, v8, v8
	v_med3_f32 v6, v2, s39, v77
	v_med3_f32 v3, v3, s39, v77
	v_mov_b32_e32 v2, v35
	v_cvt_pk_fp8_f32 v2, v6, v3
	s_waitcnt lgkmcnt(5)
	v_max_f32_e32 v4, v10, v10
	s_waitcnt lgkmcnt(4)
	v_max_f32_e32 v5, v12, v12
	v_med3_f32 v4, v4, s39, v77
	v_med3_f32 v5, v5, s39, v77
	v_cvt_pk_fp8_f32 v2, v4, v5 op_sel:[0,0,1]
	s_waitcnt lgkmcnt(3)
	v_max_f32_e32 v3, v16, v16
	s_waitcnt lgkmcnt(2)
	v_max_f32_e32 v4, v18, v18
	v_med3_f32 v8, v3, s39, v77
	v_med3_f32 v4, v4, s39, v77
	v_mov_b32_e32 v3, v35
	v_cvt_pk_fp8_f32 v3, v8, v4
	v_add_u32_e32 v8, 0x400, v59
	ds_read2_b32 v[24:25], v8 offset0:8 offset1:24
	ds_read2_b32 v[26:27], v8 offset0:41 offset1:57
	ds_read2_b32 v[28:29], v8 offset0:74 offset1:90
	ds_read2_b32 v[30:31], v8 offset0:107 offset1:123
	s_waitcnt lgkmcnt(5)
	v_max_f32_e32 v5, v20, v20
	s_waitcnt lgkmcnt(4)
	v_max_f32_e32 v6, v22, v22
	v_med3_f32 v5, v5, s39, v77
	v_med3_f32 v6, v6, s39, v77
	v_cvt_pk_fp8_f32 v3, v5, v6 op_sel:[0,0,1]
	s_waitcnt lgkmcnt(3)
	v_max_f32_e32 v4, v24, v24
	s_waitcnt lgkmcnt(2)
	v_max_f32_e32 v5, v26, v26
	v_med3_f32 v12, v4, s39, v77
	v_med3_f32 v5, v5, s39, v77
	v_mov_b32_e32 v4, v35
	v_cvt_pk_fp8_f32 v4, v12, v5
	ds_read2_b32 v[32:33], v8 offset0:140 offset1:156
	ds_read2_b32 v[80:81], v8 offset0:173 offset1:189
	ds_read2_b32 v[82:83], v8 offset0:206 offset1:222
	s_waitcnt lgkmcnt(4)
	v_max_f32_e32 v6, v28, v28
	s_waitcnt lgkmcnt(3)
	v_max_f32_e32 v10, v30, v30
	v_med3_f32 v6, v6, s39, v77
	v_med3_f32 v5, v10, s39, v77
	ds_read2_b32 v[84:85], v8 offset0:239 offset1:255
	v_cvt_pk_fp8_f32 v4, v6, v5 op_sel:[0,0,1]
	s_waitcnt lgkmcnt(3)
	v_max_f32_e32 v5, v32, v32
	s_waitcnt lgkmcnt(2)
	v_max_f32_e32 v6, v80, v80
	v_med3_f32 v8, v5, s39, v77
	v_med3_f32 v6, v6, s39, v77
	v_mov_b32_e32 v5, v35
	v_cvt_pk_fp8_f32 v5, v8, v6
	s_waitcnt lgkmcnt(1)
	v_max_f32_e32 v10, v82, v82
	s_waitcnt lgkmcnt(0)
	v_max_f32_e32 v6, v84, v84
	v_med3_f32 v8, v10, s39, v77
	v_med3_f32 v6, v6, s39, v77
	s_and_b32 s6, 0xffff, s49
	v_cvt_pk_fp8_f32 v5, v8, v6 op_sel:[0,0,1]
	s_and_b32 s16, s47, 0xffff
	v_or_b32_e32 v6, s6, v45
	v_lshl_add_u64 v[14:15], v[52:53], 0, s[16:17]
	v_lshlrev_b32_e32 v34, 10, v6
	v_lshl_add_u64 v[86:87], v[14:15], 0, v[34:35]
	v_lshl_add_u64 v[144:145], v[86:87], 0, 0
	v_mov_b32_e32 v146, v2
	v_mov_b32_e32 v147, v3
	v_mov_b32_e32 v148, v4
	v_mov_b32_e32 v149, v5
	s_nop 1
	v_max_f32_e32 v2, v7, v7
	v_max_f32_e32 v3, v9, v9
	v_med3_f32 v5, v2, s39, v77
	v_med3_f32 v3, v3, s39, v77
	v_mov_b32_e32 v2, v35
	v_cvt_pk_fp8_f32 v2, v5, v3
	v_max_f32_e32 v4, v11, v11
	v_max_f32_e32 v3, v13, v13
	v_med3_f32 v4, v4, s39, v77
	v_med3_f32 v3, v3, s39, v77
	v_cvt_pk_fp8_f32 v2, v4, v3 op_sel:[0,0,1]
	v_max_f32_e32 v3, v17, v17
	v_max_f32_e32 v4, v19, v19
	v_med3_f32 v6, v3, s39, v77
	v_med3_f32 v4, v4, s39, v77
	v_mov_b32_e32 v3, v35
	v_cvt_pk_fp8_f32 v3, v6, v4
	v_max_f32_e32 v5, v21, v21
	v_max_f32_e32 v4, v23, v23
	v_med3_f32 v5, v5, s39, v77
	v_med3_f32 v4, v4, s39, v77
	v_cvt_pk_fp8_f32 v3, v5, v4 op_sel:[0,0,1]
	v_max_f32_e32 v4, v25, v25
	v_max_f32_e32 v5, v27, v27
	v_med3_f32 v7, v4, s39, v77
	v_med3_f32 v5, v5, s39, v77
	v_mov_b32_e32 v4, v35
	v_cvt_pk_fp8_f32 v4, v7, v5
	v_max_f32_e32 v6, v29, v29
	v_max_f32_e32 v5, v31, v31
	v_med3_f32 v6, v6, s39, v77
	v_med3_f32 v5, v5, s39, v77
	v_cvt_pk_fp8_f32 v4, v6, v5 op_sel:[0,0,1]
	v_max_f32_e32 v5, v33, v33
	v_max_f32_e32 v6, v81, v81
	v_med3_f32 v8, v5, s39, v77
	v_med3_f32 v6, v6, s39, v77
	v_mov_b32_e32 v5, v35
	v_cvt_pk_fp8_f32 v5, v8, v6
	v_max_f32_e32 v7, v83, v83
	v_max_f32_e32 v6, v85, v85
	v_med3_f32 v7, v7, s39, v77
	v_med3_f32 v6, v6, s39, v77
	v_cvt_pk_fp8_f32 v5, v7, v6 op_sel:[0,0,1]
	v_or_b32_e32 v6, s6, v62
	v_lshlrev_b32_e32 v34, 10, v6
	v_lshl_add_u64 v[6:7], v[14:15], 0, v[34:35]
	v_lshl_add_u64 v[150:151], v[6:7], 0, 0
	v_mov_b32_e32 v152, v2
	v_mov_b32_e32 v153, v3
	v_mov_b32_e32 v154, v4
	v_mov_b32_e32 v155, v5
	s_mov_b64 s[74:75], -1
	s_mov_b64 s[76:77], 0
	s_waitcnt lgkmcnt(0)

.LBB0_80:
	s_mov_b32 s62, s46
	s_lshl_b32 s66, s46, 1
	s_mov_b32 s67, 0
	v_mad_u32_u24 v142, v38, s21, v44
	v_mad_u64_u32 v[140:141], s[64:65], v2, s62, v[4:5]
	global_load_dword v100, v[140:141], off
	v_lshl_add_u64 v[140:141], v[140:141], 0, s[66:67]
	global_load_dword v101, v[140:141], off
	v_lshl_add_u64 v[140:141], v[140:141], 0, s[66:67]
	global_load_dword v102, v[140:141], off
	v_lshl_add_u64 v[140:141], v[140:141], 0, s[66:67]
	global_load_dword v103, v[140:141], off
	v_lshl_add_u64 v[140:141], v[140:141], 0, s[66:67]
	global_load_dword v104, v[140:141], off
	v_lshl_add_u64 v[140:141], v[140:141], 0, s[66:67]
	global_load_dword v105, v[140:141], off
	v_lshl_add_u64 v[140:141], v[140:141], 0, s[66:67]
	global_load_dword v106, v[140:141], off
	v_lshl_add_u64 v[140:141], v[140:141], 0, s[66:67]
	global_load_dword v107, v[140:141], off
	v_lshl_add_u64 v[140:141], v[140:141], 0, s[66:67]
	global_load_dword v108, v[140:141], off
	v_lshl_add_u64 v[140:141], v[140:141], 0, s[66:67]
	global_load_dword v109, v[140:141], off
	v_lshl_add_u64 v[140:141], v[140:141], 0, s[66:67]
	global_load_dword v110, v[140:141], off
	v_lshl_add_u64 v[140:141], v[140:141], 0, s[66:67]
	global_load_dword v111, v[140:141], off
	v_lshl_add_u64 v[140:141], v[140:141], 0, s[66:67]
	global_load_dword v112, v[140:141], off
	v_lshl_add_u64 v[140:141], v[140:141], 0, s[66:67]
	global_load_dword v113, v[140:141], off
	v_lshl_add_u64 v[140:141], v[140:141], 0, s[66:67]
	global_load_dword v114, v[140:141], off
	v_lshl_add_u64 v[140:141], v[140:141], 0, s[66:67]
	global_load_dword v115, v[140:141], off
	v_lshl_add_u64 v[140:141], v[140:141], 0, s[66:67]
	global_load_dword v116, v[140:141], off
	v_lshl_add_u64 v[140:141], v[140:141], 0, s[66:67]
	global_load_dword v117, v[140:141], off
	v_lshl_add_u64 v[140:141], v[140:141], 0, s[66:67]
	global_load_dword v118, v[140:141], off
	v_lshl_add_u64 v[140:141], v[140:141], 0, s[66:67]
	global_load_dword v119, v[140:141], off
	v_lshl_add_u64 v[140:141], v[140:141], 0, s[66:67]
	global_load_dword v120, v[140:141], off
	v_lshl_add_u64 v[140:141], v[140:141], 0, s[66:67]
	global_load_dword v121, v[140:141], off
	v_lshl_add_u64 v[140:141], v[140:141], 0, s[66:67]
	global_load_dword v122, v[140:141], off
	v_lshl_add_u64 v[140:141], v[140:141], 0, s[66:67]
	global_load_dword v123, v[140:141], off
	v_lshl_add_u64 v[140:141], v[140:141], 0, s[66:67]
	global_load_dword v124, v[140:141], off
	v_lshl_add_u64 v[140:141], v[140:141], 0, s[66:67]
	global_load_dword v125, v[140:141], off
	v_lshl_add_u64 v[140:141], v[140:141], 0, s[66:67]
	global_load_dword v126, v[140:141], off
	v_lshl_add_u64 v[140:141], v[140:141], 0, s[66:67]
	global_load_dword v127, v[140:141], off
	v_lshl_add_u64 v[140:141], v[140:141], 0, s[66:67]
	global_load_dword v128, v[140:141], off
	v_lshl_add_u64 v[140:141], v[140:141], 0, s[66:67]
	global_load_dword v129, v[140:141], off
	v_lshl_add_u64 v[140:141], v[140:141], 0, s[66:67]
	global_load_dword v130, v[140:141], off
	v_lshl_add_u64 v[140:141], v[140:141], 0, s[66:67]
	global_load_dword v131, v[140:141], off
	s_and_saveexec_b64 s[70:71], s[74:75]
	global_store_dwordx4 v[144:145], v[146:149], off
	global_store_dwordx4 v[150:151], v[152:155], off
	s_mov_b64 exec, s[70:71]
	s_and_saveexec_b64 s[70:71], s[76:77]
	global_store_dwordx4 v[156:157], v[158:161], off
	global_store_dwordx4 v[162:163], v[164:167], off
	s_mov_b64 exec, s[70:71]
	s_mov_b64 s[74:75], 0
	s_mov_b64 s[76:77], 0
	s_waitcnt vmcnt(32)
	v_pk_mul_f32 v[100:101], v[100:101], s[24:25] op_sel_hi:[1,0]
	v_pk_mul_f32 v[102:103], v[102:103], s[24:25] op_sel_hi:[1,0]
	ds_write_b32 v142, v100
	ds_write_b32 v142, v101 offset:264
	ds_write_b32 v142, v102 offset:528
	ds_write_b32 v142, v103 offset:792
	s_waitcnt vmcnt(28)
	v_pk_mul_f32 v[104:105], v[104:105], s[24:25] op_sel_hi:[1,0]
	v_pk_mul_f32 v[106:107], v[106:107], s[24:25] op_sel_hi:[1,0]
	ds_write_b32 v142, v104 offset:1056
	ds_write_b32 v142, v105 offset:1320
	ds_write_b32 v142, v106 offset:1584
	ds_write_b32 v142, v107 offset:1848
	s_waitcnt vmcnt(24)
	v_pk_mul_f32 v[108:109], v[108:109], s[24:25] op_sel_hi:[1,0]
	v_pk_mul_f32 v[110:111], v[110:111], s[24:25] op_sel_hi:[1,0]
	ds_write_b32 v142, v108 offset:2112
	ds_write_b32 v142, v109 offset:2376
	ds_write_b32 v142, v110 offset:2640
	ds_write_b32 v142, v111 offset:2904
	s_waitcnt vmcnt(20)
	v_pk_mul_f32 v[112:113], v[112:113], s[24:25] op_sel_hi:[1,0]
	v_pk_mul_f32 v[114:115], v[114:115], s[24:25] op_sel_hi:[1,0]
	ds_write_b32 v142, v112 offset:3168
	ds_write_b32 v142, v113 offset:3432
	ds_write_b32 v142, v114 offset:3696
	ds_write_b32 v142, v115 offset:3960
	s_waitcnt vmcnt(16)
	v_pk_mul_f32 v[116:117], v[116:117], s[24:25] op_sel_hi:[1,0]
	v_pk_mul_f32 v[118:119], v[118:119], s[24:25] op_sel_hi:[1,0]
	ds_write_b32 v142, v116 offset:4224
	ds_write_b32 v142, v117 offset:4488
	ds_write_b32 v142, v118 offset:4752
	ds_write_b32 v142, v119 offset:5016
	s_waitcnt vmcnt(12)
	v_pk_mul_f32 v[120:121], v[120:121], s[24:25] op_sel_hi:[1,0]
	v_pk_mul_f32 v[122:123], v[122:123], s[24:25] op_sel_hi:[1,0]
	ds_write_b32 v142, v120 offset:5280
	ds_write_b32 v142, v121 offset:5544
	ds_write_b32 v142, v122 offset:5808
	ds_write_b32 v142, v123 offset:6072
	s_waitcnt vmcnt(8)
	v_pk_mul_f32 v[124:125], v[124:125], s[24:25] op_sel_hi:[1,0]
	v_pk_mul_f32 v[126:127], v[126:127], s[24:25] op_sel_hi:[1,0]
	ds_write_b32 v142, v124 offset:6336
	ds_write_b32 v142, v125 offset:6600
	ds_write_b32 v142, v126 offset:6864
	ds_write_b32 v142, v127 offset:7128
	s_waitcnt vmcnt(4)
	v_pk_mul_f32 v[128:129], v[128:129], s[24:25] op_sel_hi:[1,0]
	v_pk_mul_f32 v[130:131], v[130:131], s[24:25] op_sel_hi:[1,0]
	ds_write_b32 v142, v128 offset:7392
	ds_write_b32 v142, v129 offset:7656
	ds_write_b32 v142, v130 offset:7920
	ds_write_b32 v142, v131 offset:8184
	s_waitcnt lgkmcnt(0)
	ds_read2_b32 v[8:9], v59 offset1:16
	ds_read2_b32 v[10:11], v59 offset0:33 offset1:49
	ds_read2_b32 v[12:13], v59 offset0:66 offset1:82
	ds_read2_b32 v[14:15], v59 offset0:99 offset1:115
	ds_read2_b32 v[18:19], v59 offset0:132 offset1:148
	ds_read2_b32 v[20:21], v59 offset0:165 offset1:181
	ds_read2_b32 v[22:23], v59 offset0:198 offset1:214
	ds_read2_b32 v[24:25], v59 offset0:231 offset1:247
	s_waitcnt lgkmcnt(7)
	v_max_f32_e32 v4, v8, v8
	s_waitcnt lgkmcnt(6)
	v_max_f32_e32 v5, v10, v10
	v_med3_f32 v8, v4, s39, v77
	v_med3_f32 v5, v5, s39, v77
	v_mov_b32_e32 v4, v35
	v_cvt_pk_fp8_f32 v4, v8, v5
	s_waitcnt lgkmcnt(5)
	v_max_f32_e32 v6, v12, v12
	s_waitcnt lgkmcnt(4)
	v_max_f32_e32 v7, v14, v14
	v_med3_f32 v6, v6, s39, v77
	v_med3_f32 v7, v7, s39, v77
	v_cvt_pk_fp8_f32 v4, v6, v7 op_sel:[0,0,1]
	s_waitcnt lgkmcnt(3)
	v_max_f32_e32 v5, v18, v18
	s_waitcnt lgkmcnt(2)
	v_max_f32_e32 v6, v20, v20
	v_med3_f32 v10, v5, s39, v77
	v_med3_f32 v6, v6, s39, v77
	v_mov_b32_e32 v5, v35
	v_cvt_pk_fp8_f32 v5, v10, v6
	v_add_u32_e32 v10, 0x400, v59
	ds_read2_b32 v[26:27], v10 offset0:8 offset1:24
	ds_read2_b32 v[28:29], v10 offset0:41 offset1:57
	ds_read2_b32 v[30:31], v10 offset0:74 offset1:90
	ds_read2_b32 v[32:33], v10 offset0:107 offset1:123
	s_waitcnt lgkmcnt(5)
	v_max_f32_e32 v7, v22, v22
	s_waitcnt lgkmcnt(4)
	v_max_f32_e32 v8, v24, v24
	v_med3_f32 v7, v7, s39, v77
	v_med3_f32 v8, v8, s39, v77
	v_cvt_pk_fp8_f32 v5, v7, v8 op_sel:[0,0,1]
	s_waitcnt lgkmcnt(3)
	v_max_f32_e32 v6, v26, v26
	s_waitcnt lgkmcnt(2)
	v_max_f32_e32 v7, v28, v28
	v_med3_f32 v14, v6, s39, v77
	v_med3_f32 v7, v7, s39, v77
	v_mov_b32_e32 v6, v35
	v_cvt_pk_fp8_f32 v6, v14, v7
	ds_read2_b32 v[80:81], v10 offset0:140 offset1:156
	ds_read2_b32 v[82:83], v10 offset0:173 offset1:189
	ds_read2_b32 v[84:85], v10 offset0:206 offset1:222
	s_waitcnt lgkmcnt(4)
	v_max_f32_e32 v8, v30, v30
	s_waitcnt lgkmcnt(3)
	v_max_f32_e32 v12, v32, v32
	v_med3_f32 v8, v8, s39, v77
	v_med3_f32 v7, v12, s39, v77
	ds_read2_b32 v[86:87], v10 offset0:239 offset1:255
	v_cvt_pk_fp8_f32 v6, v8, v7 op_sel:[0,0,1]
	s_waitcnt lgkmcnt(3)
	v_max_f32_e32 v7, v80, v80
	s_waitcnt lgkmcnt(2)
	v_max_f32_e32 v8, v82, v82
	v_med3_f32 v10, v7, s39, v77
	v_med3_f32 v8, v8, s39, v77
	v_mov_b32_e32 v7, v35
	v_cvt_pk_fp8_f32 v7, v10, v8
	s_waitcnt lgkmcnt(1)
	v_max_f32_e32 v12, v84, v84
	s_waitcnt lgkmcnt(0)
	v_max_f32_e32 v8, v86, v86
	v_med3_f32 v10, v12, s39, v77
	v_med3_f32 v8, v8, s39, v77
	v_cvt_pk_fp8_f32 v7, v10, v8 op_sel:[0,0,1]
	s_ashr_i32 s9, s8, 31
	v_or_b32_e32 v34, s6, v45
	v_lshl_add_u64 v[16:17], v[54:55], 0, s[8:9]
	v_lshlrev_b64 v[88:89], 12, v[34:35]
	v_lshl_add_u64 v[88:89], v[16:17], 0, v[88:89]
	v_lshl_add_u64 v[144:145], v[88:89], 0, 0
	v_mov_b32_e32 v146, v4
	v_mov_b32_e32 v147, v5
	v_mov_b32_e32 v148, v6
	v_mov_b32_e32 v149, v7
	v_or_b32_e32 v34, s6, v62
	s_mov_b64 s[26:27], 0
	v_max_f32_e32 v4, v9, v9
	v_max_f32_e32 v5, v11, v11
	v_med3_f32 v7, v4, s39, v77
	v_med3_f32 v5, v5, s39, v77
	v_mov_b32_e32 v4, v35
	v_cvt_pk_fp8_f32 v4, v7, v5
	v_max_f32_e32 v6, v13, v13
	v_max_f32_e32 v5, v15, v15
	v_med3_f32 v6, v6, s39, v77
	v_med3_f32 v5, v5, s39, v77
	v_cvt_pk_fp8_f32 v4, v6, v5 op_sel:[0,0,1]
	v_max_f32_e32 v5, v19, v19
	v_max_f32_e32 v6, v21, v21
	v_med3_f32 v8, v5, s39, v77
	v_med3_f32 v6, v6, s39, v77
	v_mov_b32_e32 v5, v35
	v_cvt_pk_fp8_f32 v5, v8, v6
	v_max_f32_e32 v7, v23, v23
	v_max_f32_e32 v6, v25, v25
	v_med3_f32 v7, v7, s39, v77
	v_med3_f32 v6, v6, s39, v77
	v_cvt_pk_fp8_f32 v5, v7, v6 op_sel:[0,0,1]
	v_max_f32_e32 v6, v27, v27
	v_max_f32_e32 v7, v29, v29
	v_med3_f32 v9, v6, s39, v77
	v_med3_f32 v7, v7, s39, v77
	v_mov_b32_e32 v6, v35
	v_cvt_pk_fp8_f32 v6, v9, v7
	v_max_f32_e32 v8, v31, v31
	v_max_f32_e32 v7, v33, v33
	v_med3_f32 v8, v8, s39, v77
	v_med3_f32 v7, v7, s39, v77
	v_cvt_pk_fp8_f32 v6, v8, v7 op_sel:[0,0,1]
	v_max_f32_e32 v7, v81, v81
	v_max_f32_e32 v8, v83, v83
	v_med3_f32 v10, v7, s39, v77
	v_med3_f32 v8, v8, s39, v77
	v_mov_b32_e32 v7, v35
	v_cvt_pk_fp8_f32 v7, v10, v8
	v_max_f32_e32 v9, v85, v85
	v_max_f32_e32 v8, v87, v87
	v_med3_f32 v9, v9, s39, v77
	v_med3_f32 v8, v8, s39, v77
	v_cvt_pk_fp8_f32 v7, v9, v8 op_sel:[0,0,1]
	v_lshlrev_b64 v[8:9], 12, v[34:35]
	v_lshl_add_u64 v[8:9], v[16:17], 0, v[8:9]
	v_lshl_add_u64 v[150:151], v[8:9], 0, 0
	v_mov_b32_e32 v152, v4
	v_mov_b32_e32 v153, v5
	v_mov_b32_e32 v154, v6
	v_mov_b32_e32 v155, v7
	s_mov_b64 s[74:75], -1
	s_mov_b64 s[76:77], 0
	s_waitcnt lgkmcnt(0)

.LBB0_84:
	s_mov_b32 s62, s46
	s_lshl_b32 s66, s46, 1
	s_mov_b32 s67, 0
	v_mad_u32_u24 v142, v38, s21, v44
	v_mad_u64_u32 v[140:141], s[64:65], v2, s62, v[4:5]
	global_load_dword v100, v[140:141], off
	v_lshl_add_u64 v[140:141], v[140:141], 0, s[66:67]
	global_load_dword v101, v[140:141], off
	v_lshl_add_u64 v[140:141], v[140:141], 0, s[66:67]
	global_load_dword v102, v[140:141], off
	v_lshl_add_u64 v[140:141], v[140:141], 0, s[66:67]
	global_load_dword v103, v[140:141], off
	v_lshl_add_u64 v[140:141], v[140:141], 0, s[66:67]
	global_load_dword v104, v[140:141], off
	v_lshl_add_u64 v[140:141], v[140:141], 0, s[66:67]
	global_load_dword v105, v[140:141], off
	v_lshl_add_u64 v[140:141], v[140:141], 0, s[66:67]
	global_load_dword v106, v[140:141], off
	v_lshl_add_u64 v[140:141], v[140:141], 0, s[66:67]
	global_load_dword v107, v[140:141], off
	v_lshl_add_u64 v[140:141], v[140:141], 0, s[66:67]
	global_load_dword v108, v[140:141], off
	v_lshl_add_u64 v[140:141], v[140:141], 0, s[66:67]
	global_load_dword v109, v[140:141], off
	v_lshl_add_u64 v[140:141], v[140:141], 0, s[66:67]
	global_load_dword v110, v[140:141], off
	v_lshl_add_u64 v[140:141], v[140:141], 0, s[66:67]
	global_load_dword v111, v[140:141], off
	v_lshl_add_u64 v[140:141], v[140:141], 0, s[66:67]
	global_load_dword v112, v[140:141], off
	v_lshl_add_u64 v[140:141], v[140:141], 0, s[66:67]
	global_load_dword v113, v[140:141], off
	v_lshl_add_u64 v[140:141], v[140:141], 0, s[66:67]
	global_load_dword v114, v[140:141], off
	v_lshl_add_u64 v[140:141], v[140:141], 0, s[66:67]
	global_load_dword v115, v[140:141], off
	v_lshl_add_u64 v[140:141], v[140:141], 0, s[66:67]
	global_load_dword v116, v[140:141], off
	v_lshl_add_u64 v[140:141], v[140:141], 0, s[66:67]
	global_load_dword v117, v[140:141], off
	v_lshl_add_u64 v[140:141], v[140:141], 0, s[66:67]
	global_load_dword v118, v[140:141], off
	v_lshl_add_u64 v[140:141], v[140:141], 0, s[66:67]
	global_load_dword v119, v[140:141], off
	v_lshl_add_u64 v[140:141], v[140:141], 0, s[66:67]
	global_load_dword v120, v[140:141], off
	v_lshl_add_u64 v[140:141], v[140:141], 0, s[66:67]
	global_load_dword v121, v[140:141], off
	v_lshl_add_u64 v[140:141], v[140:141], 0, s[66:67]
	global_load_dword v122, v[140:141], off
	v_lshl_add_u64 v[140:141], v[140:141], 0, s[66:67]
	global_load_dword v123, v[140:141], off
	v_lshl_add_u64 v[140:141], v[140:141], 0, s[66:67]
	global_load_dword v124, v[140:141], off
	v_lshl_add_u64 v[140:141], v[140:141], 0, s[66:67]
	global_load_dword v125, v[140:141], off
	v_lshl_add_u64 v[140:141], v[140:141], 0, s[66:67]
	global_load_dword v126, v[140:141], off
	v_lshl_add_u64 v[140:141], v[140:141], 0, s[66:67]
	global_load_dword v127, v[140:141], off
	v_lshl_add_u64 v[140:141], v[140:141], 0, s[66:67]
	global_load_dword v128, v[140:141], off
	v_lshl_add_u64 v[140:141], v[140:141], 0, s[66:67]
	global_load_dword v129, v[140:141], off
	v_lshl_add_u64 v[140:141], v[140:141], 0, s[66:67]
	global_load_dword v130, v[140:141], off
	v_lshl_add_u64 v[140:141], v[140:141], 0, s[66:67]
	global_load_dword v131, v[140:141], off
	s_and_saveexec_b64 s[70:71], s[74:75]
	global_store_dwordx4 v[144:145], v[146:149], off
	global_store_dwordx4 v[150:151], v[152:155], off
	s_mov_b64 exec, s[70:71]
	s_and_saveexec_b64 s[70:71], s[76:77]
	global_store_dwordx4 v[156:157], v[158:161], off
	global_store_dwordx4 v[162:163], v[164:167], off
	s_mov_b64 exec, s[70:71]
	s_mov_b64 s[74:75], 0
	s_mov_b64 s[76:77], 0
	s_waitcnt vmcnt(32)
	ds_write_b32 v142, v100
	ds_write_b32 v142, v101 offset:264
	ds_write_b32 v142, v102 offset:528
	ds_write_b32 v142, v103 offset:792
	s_waitcnt vmcnt(28)
	ds_write_b32 v142, v104 offset:1056
	ds_write_b32 v142, v105 offset:1320
	ds_write_b32 v142, v106 offset:1584
	ds_write_b32 v142, v107 offset:1848
	s_waitcnt vmcnt(24)
	ds_write_b32 v142, v108 offset:2112
	ds_write_b32 v142, v109 offset:2376
	ds_write_b32 v142, v110 offset:2640
	ds_write_b32 v142, v111 offset:2904
	s_waitcnt vmcnt(20)
	ds_write_b32 v142, v112 offset:3168
	ds_write_b32 v142, v113 offset:3432
	ds_write_b32 v142, v114 offset:3696
	ds_write_b32 v142, v115 offset:3960
	s_waitcnt vmcnt(16)
	ds_write_b32 v142, v116 offset:4224
	ds_write_b32 v142, v117 offset:4488
	ds_write_b32 v142, v118 offset:4752
	ds_write_b32 v142, v119 offset:5016
	s_waitcnt vmcnt(12)
	ds_write_b32 v142, v120 offset:5280
	ds_write_b32 v142, v121 offset:5544
	ds_write_b32 v142, v122 offset:5808
	ds_write_b32 v142, v123 offset:6072
	s_waitcnt vmcnt(8)
	ds_write_b32 v142, v124 offset:6336
	ds_write_b32 v142, v125 offset:6600
	ds_write_b32 v142, v126 offset:6864
	ds_write_b32 v142, v127 offset:7128
	s_waitcnt vmcnt(4)
	ds_write_b32 v142, v128 offset:7392
	ds_write_b32 v142, v129 offset:7656
	ds_write_b32 v142, v130 offset:7920
	ds_write_b32 v142, v131 offset:8184
	s_waitcnt lgkmcnt(0)
	ds_read2_b32 v[6:7], v65 offset1:8
	ds_read2_b32 v[10:11], v65 offset0:33 offset1:41
	ds_read2_b32 v[12:13], v65 offset0:66 offset1:74
	ds_read2_b32 v[14:15], v65 offset0:99 offset1:107
	ds_read2_b32 v[16:17], v65 offset0:132 offset1:140
	ds_read2_b32 v[18:19], v65 offset0:165 offset1:173
	s_waitcnt lgkmcnt(5)
	v_bfe_u32 v2, v6, 16, 1
	v_add3_u32 v2, v6, v2, s41
	s_waitcnt lgkmcnt(4)
	v_bfe_u32 v3, v10, 16, 1
	v_lshrrev_b32_e32 v2, 16, v2
	v_add3_u32 v3, v10, v3, s41
	v_and_or_b32 v2, v3, s42, v2
	s_waitcnt lgkmcnt(3)
	v_bfe_u32 v3, v12, 16, 1
	v_add3_u32 v3, v12, v3, s41
	s_waitcnt lgkmcnt(2)
	v_bfe_u32 v4, v14, 16, 1
	ds_read2_b32 v[20:21], v65 offset0:198 offset1:206
	v_lshrrev_b32_e32 v3, 16, v3
	v_add3_u32 v4, v14, v4, s41
	ds_read2_b32 v[22:23], v65 offset0:231 offset1:239
	v_and_or_b32 v3, v4, s42, v3
	s_waitcnt lgkmcnt(3)
	v_bfe_u32 v4, v16, 16, 1
	v_add3_u32 v4, v16, v4, s41
	s_waitcnt lgkmcnt(2)
	v_bfe_u32 v5, v18, 16, 1
	v_lshrrev_b32_e32 v4, 16, v4
	v_add3_u32 v5, v18, v5, s41
	v_and_or_b32 v4, v5, s42, v4
	s_waitcnt lgkmcnt(1)
	v_bfe_u32 v5, v20, 16, 1
	v_or_b32_e32 v24, s6, v64
	s_ashr_i32 s9, s8, 31
	v_add3_u32 v5, v20, v5, s41
	s_waitcnt lgkmcnt(0)
	v_bfe_u32 v6, v22, 16, 1
	v_ashrrev_i32_e32 v25, 31, v24
	v_lshl_add_u64 v[8:9], s[8:9], 1, v[56:57]
	v_lshrrev_b32_e32 v5, 16, v5
	v_add3_u32 v6, v22, v6, s41
	v_lshlrev_b64 v[24:25], 13, v[24:25]
	v_and_or_b32 v5, v6, s42, v5
	v_lshl_add_u64 v[24:25], v[8:9], 0, v[24:25]
	v_lshl_add_u64 v[144:145], v[24:25], 0, 0
	v_mov_b32_e32 v146, v2
	v_mov_b32_e32 v147, v3
	v_mov_b32_e32 v148, v4
	v_mov_b32_e32 v149, v5
	v_bfe_u32 v6, v23, 16, 1
	v_add3_u32 v6, v23, v6, s41
	v_bfe_u32 v2, v7, 16, 1
	v_add3_u32 v2, v7, v2, s41
	v_bfe_u32 v3, v11, 16, 1
	v_lshrrev_b32_e32 v2, 16, v2
	v_add3_u32 v3, v11, v3, s41
	v_and_or_b32 v2, v3, s42, v2
	v_bfe_u32 v3, v13, 16, 1
	v_add3_u32 v3, v13, v3, s41
	v_bfe_u32 v4, v15, 16, 1
	v_lshrrev_b32_e32 v3, 16, v3
	v_add3_u32 v4, v15, v4, s41
	v_and_or_b32 v3, v4, s42, v3
	v_bfe_u32 v4, v17, 16, 1
	v_add3_u32 v4, v17, v4, s41
	v_bfe_u32 v5, v19, 16, 1
	v_lshrrev_b32_e32 v4, 16, v4
	v_add3_u32 v5, v19, v5, s41
	v_and_or_b32 v4, v5, s42, v4
	v_bfe_u32 v5, v21, 16, 1
	v_add3_u32 v5, v21, v5, s41
	v_lshrrev_b32_e32 v5, 16, v5
	v_and_or_b32 v5, v6, s42, v5
	v_or_b32_e32 v6, s6, v66
	v_ashrrev_i32_e32 v7, 31, v6
	v_lshlrev_b64 v[6:7], 13, v[6:7]
	ds_read2_b32 v[10:11], v65 offset0:16 offset1:24
	v_lshl_add_u64 v[6:7], v[8:9], 0, v[6:7]
	v_lshl_add_u64 v[150:151], v[6:7], 0, 0
	v_mov_b32_e32 v152, v2
	v_mov_b32_e32 v153, v3
	v_mov_b32_e32 v154, v4
	v_mov_b32_e32 v155, v5
	ds_read2_b32 v[6:7], v65 offset0:49 offset1:57
	ds_read2_b32 v[12:13], v65 offset0:82 offset1:90
	ds_read2_b32 v[14:15], v65 offset0:115 offset1:123
	s_waitcnt lgkmcnt(3)
	v_bfe_u32 v2, v10, 16, 1
	v_add3_u32 v2, v10, v2, s41
	s_waitcnt lgkmcnt(2)
	v_bfe_u32 v3, v6, 16, 1
	ds_read2_b32 v[16:17], v65 offset0:148 offset1:156
	v_lshrrev_b32_e32 v2, 16, v2
	v_add3_u32 v3, v6, v3, s41
	ds_read2_b32 v[18:19], v65 offset0:181 offset1:189
	v_and_or_b32 v2, v3, s42, v2
	s_waitcnt lgkmcnt(3)
	v_bfe_u32 v3, v12, 16, 1
	v_add3_u32 v3, v12, v3, s41
	s_waitcnt lgkmcnt(2)
	v_bfe_u32 v4, v14, 16, 1
	ds_read2_b32 v[20:21], v65 offset0:214 offset1:222
	v_lshrrev_b32_e32 v3, 16, v3
	v_add3_u32 v4, v14, v4, s41
	ds_read2_b32 v[22:23], v65 offset0:247 offset1:255
	v_and_or_b32 v3, v4, s42, v3
	s_waitcnt lgkmcnt(3)
	v_bfe_u32 v4, v16, 16, 1
	v_add3_u32 v4, v16, v4, s41
	s_waitcnt lgkmcnt(2)
	v_bfe_u32 v5, v18, 16, 1
	v_lshrrev_b32_e32 v4, 16, v4
	v_add3_u32 v5, v18, v5, s41
	v_and_or_b32 v4, v5, s42, v4
	s_waitcnt lgkmcnt(1)
	v_bfe_u32 v5, v20, 16, 1
	v_or_b32_e32 v24, s6, v67
	v_add3_u32 v5, v20, v5, s41
	s_waitcnt lgkmcnt(0)
	v_bfe_u32 v6, v22, 16, 1
	v_ashrrev_i32_e32 v25, 31, v24
	v_lshrrev_b32_e32 v5, 16, v5
	v_add3_u32 v6, v22, v6, s41
	v_lshlrev_b64 v[24:25], 13, v[24:25]
	v_and_or_b32 v5, v6, s42, v5
	v_lshl_add_u64 v[24:25], v[8:9], 0, v[24:25]
	v_lshl_add_u64 v[156:157], v[24:25], 0, 0
	v_mov_b32_e32 v158, v2
	v_mov_b32_e32 v159, v3
	v_mov_b32_e32 v160, v4
	v_mov_b32_e32 v161, v5
	v_bfe_u32 v6, v23, 16, 1
	v_add3_u32 v6, v23, v6, s41
	v_bfe_u32 v2, v11, 16, 1
	v_add3_u32 v2, v11, v2, s41
	v_bfe_u32 v3, v7, 16, 1
	v_lshrrev_b32_e32 v2, 16, v2
	v_add3_u32 v3, v7, v3, s41
	v_and_or_b32 v2, v3, s42, v2
	v_bfe_u32 v3, v13, 16, 1
	v_add3_u32 v3, v13, v3, s41
	v_bfe_u32 v4, v15, 16, 1
	v_lshrrev_b32_e32 v3, 16, v3
	v_add3_u32 v4, v15, v4, s41
	v_and_or_b32 v3, v4, s42, v3
	v_bfe_u32 v4, v17, 16, 1
	v_add3_u32 v4, v17, v4, s41
	v_bfe_u32 v5, v19, 16, 1
	v_lshrrev_b32_e32 v4, 16, v4
	v_add3_u32 v5, v19, v5, s41
	v_and_or_b32 v4, v5, s42, v4
	v_bfe_u32 v5, v21, 16, 1
	v_add3_u32 v5, v21, v5, s41
	v_lshrrev_b32_e32 v5, 16, v5
	v_and_or_b32 v5, v6, s42, v5
	v_or_b32_e32 v6, s6, v68
	v_ashrrev_i32_e32 v7, 31, v6
	v_lshlrev_b64 v[6:7], 13, v[6:7]
	v_lshl_add_u64 v[6:7], v[8:9], 0, v[6:7]
	v_lshl_add_u64 v[162:163], v[6:7], 0, 0
	v_mov_b32_e32 v164, v2
	v_mov_b32_e32 v165, v3
	v_mov_b32_e32 v166, v4
	v_mov_b32_e32 v167, v5
	s_mov_b64 s[74:75], -1
	s_mov_b64 s[76:77], -1
	s_waitcnt lgkmcnt(0)
	s_branch .LBB0_11
.LBB0_86:
	s_and_saveexec_b64 s[70:71], s[74:75]
	global_store_dwordx4 v[144:145], v[146:149], off
	global_store_dwordx4 v[150:151], v[152:155], off
	s_mov_b64 exec, s[70:71]
	s_and_saveexec_b64 s[70:71], s[76:77]
	global_store_dwordx4 v[156:157], v[158:161], off
	global_store_dwordx4 v[162:163], v[164:167], off
	s_mov_b64 exec, s[70:71]
	s_mov_b64 s[74:75], 0
	s_mov_b64 s[76:77], 0
	s_ashr_i32 s49, s48, 31
	s_lshl_b64 s[4:5], s[48:49], 9
	v_ashrrev_i32_e32 v37, 31, v36
	v_lshl_add_u64 v[6:7], s[4:5], 0, v[36:37]
	s_mov_b64 s[4:5], 0xc000
	v_cmp_gt_u64_e32 vcc, s[4:5], v[6:7]
	s_and_saveexec_b64 s[6:7], vcc
	s_cbranch_execz .LBB0_89
	s_ashr_i32 s35, s34, 31
	s_lshl_b64 s[8:9], s[34:35], 9
	s_lshl_b64 s[4:5], s[48:49], 13
	s_waitcnt lgkmcnt(0)
	s_add_u32 s4, s14, s4
	s_addc_u32 s5, s15, s5
	v_lshl_add_u64 v[2:3], v[36:37], 4, s[4:5]
	s_mov_b64 s[4:5], 0x46a40000
	v_lshl_add_u64 v[8:9], v[2:3], 0, s[4:5]
	v_mov_b32_e32 v2, 0
	s_lshl_b64 s[10:11], s[34:35], 13
	s_mov_b64 s[16:17], 0
	v_mov_b32_e32 v3, v2
	v_mov_b32_e32 v4, v2
	v_mov_b32_e32 v5, v2
	s_mov_b64 s[18:19], 0xbfff
